# residual GEMM epilogue fused with the following RMS norm for the latent-only phases (layer-1 w_out -> ffn2 norm; last ffn2_out -> final norm): panel-wise sum-of-squares exchange through d_ws, norm pha
# baseline (speedup 1.0000x reference)
.LBB0_220:
	s_min_i32 s13, s43, 64
	s_ashr_i32 s13, s13, 4
	s_mul_hi_i32 s23, s13, 0x9000
	s_mul_i32 s13, s13, 0x9000
	s_add_u32 s28, s53, s13
	v_lshl_or_b32 v154, s58, 8, v183
	s_addc_u32 s29, s94, s23
	v_ashrrev_i32_e32 v155, 31, v154
	v_lshl_add_u64 v[162:163], v[154:155], 2, s[28:29]
	s_cmp_lg_u32 s42, 0
	s_cbranch_scc1 .Lres_slow
	s_and_b64 vcc, exec, s[38:39]
	s_cbranch_vccz .Lres_slow
	s_cmpk_lg_i32 s46, 0x100
	s_cbranch_scc1 .Lres_slow
	s_and_b64 vcc, exec, s[20:21]
	s_cbranch_vccz .Lres_slow
	s_cmp_eq_u32 s3, 16
	s_cbranch_scc1 .Lrf_go
	s_cmp_eq_u32 s3, 19
	s_cbranch_scc1 .Lrf_go
	s_branch .Lres_slow
.Lrf_go:
	s_load_dwordx2 s[40:41], s[0:1], 0xa0
	global_load_dwordx4 v[236:239], v[162:163], off
	global_load_dwordx4 v[240:243], v[162:163], off offset:16
	global_load_dwordx4 v[168:171], v[162:163], off offset:512
	global_load_dwordx4 v[156:159], v[162:163], off offset:528
	s_lshl_b32 s13, s43, 8
	v_add_u32_e32 v162, s13, v174
	v_ashrrev_i32_e32 v163, 31, v162
	v_lshlrev_b64 v[162:163], 10, v[162:163]
	v_lshl_add_u64 v[162:163], v[162:163], 0, v[154:155]
	v_mov_b32_e32 v145, v162
	v_mov_b32_e32 v185, v163
	v_lshl_add_u64 v[222:223], v[162:163], 1, s[16:17]
	v_mov_b64_e32 v[154:155], v[222:223]
	s_mov_b64 vcc, 0x8000
	s_mov_b64 s[28:29], 0x20000
	s_cmp_eq_u32 s3, 19
	s_cbranch_scc1 .Lrf_last
	global_load_dwordx4 v[186:189], v[222:223], off
	global_load_dwordx4 v[190:193], v[222:223], off offset:256
	v_lshl_add_u64 v[222:223], v[222:223], 0, vcc
	global_load_dwordx4 v[194:197], v[222:223], off
	global_load_dwordx4 v[198:201], v[222:223], off offset:256
	v_lshl_add_u64 v[222:223], v[222:223], 0, vcc
	global_load_dwordx4 v[202:205], v[222:223], off
	global_load_dwordx4 v[206:209], v[222:223], off offset:256
	v_lshl_add_u64 v[222:223], v[222:223], 0, vcc
	global_load_dwordx4 v[210:213], v[222:223], off
	global_load_dwordx4 v[214:217], v[222:223], off offset:256
	v_lshl_add_u64 v[222:223], v[222:223], 0, vcc
	v_lshl_add_u64 v[222:223], v[222:223], 0, s[28:29]
	global_load_dwordx4 v[218:221], v[222:223], off
	global_load_dwordx4 v[164:167], v[222:223], off offset:256
	v_lshl_add_u64 v[222:223], v[222:223], 0, vcc
	s_waitcnt vmcnt(9)
	v_pk_mul_f32 v[236:237], v[146:147], v[236:237]
	v_pk_mul_f32 v[238:239], v[146:147], v[238:239]
	v_pk_mul_f32 v[240:241], v[146:147], v[240:241]
	v_pk_mul_f32 v[242:243], v[146:147], v[242:243]
	v_pk_mul_f32 v[168:169], v[146:147], v[168:169]
	v_pk_mul_f32 v[170:171], v[146:147], v[170:171]
	v_pk_mul_f32 v[156:157], v[146:147], v[156:157]
	v_pk_mul_f32 v[158:159], v[146:147], v[158:159]
	v_lshlrev_b32_e32 v152, 16, v186
	v_and_b32_e32 v153, 0xffff0000, v186
	v_lshlrev_b32_e32 v160, 16, v187
	v_and_b32_e32 v161, 0xffff0000, v187
	v_lshlrev_b32_e32 v172, 16, v188
	v_and_b32_e32 v173, 0xffff0000, v188
	v_lshlrev_b32_e32 v162, 16, v189
	v_and_b32_e32 v163, 0xffff0000, v189
	global_load_dwordx4 v[186:189], v[222:223], off
	v_pk_mul_f32 v[126:127], v[126:127], v[236:237]
	v_pk_mul_f32 v[128:129], v[128:129], v[238:239]
	v_pk_mul_f32 v[122:123], v[122:123], v[240:241]
	v_pk_mul_f32 v[124:125], v[124:125], v[242:243]
	v_pk_add_f32 v[126:127], v[126:127], v[152:153]
	v_pk_add_f32 v[128:129], v[128:129], v[160:161]
	v_pk_add_f32 v[122:123], v[122:123], v[172:173]
	v_pk_add_f32 v[124:125], v[124:125], v[162:163]
	v_pk_mul_f32 v[152:153], v[126:127], v[126:127]
	v_pk_fma_f32 v[152:153], v[128:129], v[128:129], v[152:153]
	v_pk_fma_f32 v[152:153], v[122:123], v[122:123], v[152:153]
	v_pk_fma_f32 v[152:153], v[124:125], v[124:125], v[152:153]
	v_add_f32_e32 v130, v152, v153
	v_cvt_pk_bf16_f32 v244, v126, v127
	v_cvt_pk_bf16_f32 v245, v128, v129
	v_cvt_pk_bf16_f32 v246, v122, v123
	v_cvt_pk_bf16_f32 v247, v124, v125
	global_store_dwordx4 v[154:155], v[244:247], off sc1
	s_waitcnt vmcnt(10)
	v_lshlrev_b32_e32 v152, 16, v190
	v_and_b32_e32 v153, 0xffff0000, v190
	v_lshlrev_b32_e32 v160, 16, v191
	v_and_b32_e32 v161, 0xffff0000, v191
	v_lshlrev_b32_e32 v172, 16, v192
	v_and_b32_e32 v173, 0xffff0000, v192
	v_lshlrev_b32_e32 v162, 16, v193
	v_and_b32_e32 v163, 0xffff0000, v193
	global_load_dwordx4 v[190:193], v[222:223], off offset:256
	v_lshl_add_u64 v[222:223], v[222:223], 0, vcc
	v_pk_mul_f32 v[118:119], v[118:119], v[168:169]
	v_pk_mul_f32 v[120:121], v[120:121], v[170:171]
	v_pk_mul_f32 v[114:115], v[114:115], v[156:157]
	v_pk_mul_f32 v[116:117], v[116:117], v[158:159]
	v_pk_add_f32 v[118:119], v[118:119], v[152:153]
	v_pk_add_f32 v[120:121], v[120:121], v[160:161]
	v_pk_add_f32 v[114:115], v[114:115], v[172:173]
	v_pk_add_f32 v[116:117], v[116:117], v[162:163]
	v_pk_mul_f32 v[152:153], v[118:119], v[118:119]
	v_pk_fma_f32 v[152:153], v[120:121], v[120:121], v[152:153]
	v_pk_fma_f32 v[152:153], v[114:115], v[114:115], v[152:153]
	v_pk_fma_f32 v[152:153], v[116:117], v[116:117], v[152:153]
	v_add_f32_e32 v152, v152, v153
	v_add_f32_e32 v130, v130, v152
	v_cvt_pk_bf16_f32 v244, v118, v119
	v_cvt_pk_bf16_f32 v245, v120, v121
	v_cvt_pk_bf16_f32 v246, v114, v115
	v_cvt_pk_bf16_f32 v247, v116, v117
	global_store_dwordx4 v[154:155], v[244:247], off offset:256 sc1
	v_lshl_add_u64 v[154:155], v[154:155], 0, vcc
	s_waitcnt vmcnt(11)
	v_lshlrev_b32_e32 v152, 16, v194
	v_and_b32_e32 v153, 0xffff0000, v194
	v_lshlrev_b32_e32 v160, 16, v195
	v_and_b32_e32 v161, 0xffff0000, v195
	v_lshlrev_b32_e32 v172, 16, v196
	v_and_b32_e32 v173, 0xffff0000, v196
	v_lshlrev_b32_e32 v162, 16, v197
	v_and_b32_e32 v163, 0xffff0000, v197
	global_load_dwordx4 v[194:197], v[222:223], off
	v_pk_mul_f32 v[110:111], v[110:111], v[236:237]
	v_pk_mul_f32 v[112:113], v[112:113], v[238:239]
	v_pk_mul_f32 v[106:107], v[106:107], v[240:241]
	v_pk_mul_f32 v[108:109], v[108:109], v[242:243]
	v_pk_add_f32 v[110:111], v[110:111], v[152:153]
	v_pk_add_f32 v[112:113], v[112:113], v[160:161]
	v_pk_add_f32 v[106:107], v[106:107], v[172:173]
	v_pk_add_f32 v[108:109], v[108:109], v[162:163]
	v_pk_mul_f32 v[152:153], v[110:111], v[110:111]
	v_pk_fma_f32 v[152:153], v[112:113], v[112:113], v[152:153]
	v_pk_fma_f32 v[152:153], v[106:107], v[106:107], v[152:153]
	v_pk_fma_f32 v[152:153], v[108:109], v[108:109], v[152:153]
	v_add_f32_e32 v131, v152, v153
	v_cvt_pk_bf16_f32 v244, v110, v111
	v_cvt_pk_bf16_f32 v245, v112, v113
	v_cvt_pk_bf16_f32 v246, v106, v107
	v_cvt_pk_bf16_f32 v247, v108, v109
	global_store_dwordx4 v[154:155], v[244:247], off sc1
	s_waitcnt vmcnt(12)
	v_lshlrev_b32_e32 v152, 16, v198
	v_and_b32_e32 v153, 0xffff0000, v198
	v_lshlrev_b32_e32 v160, 16, v199
	v_and_b32_e32 v161, 0xffff0000, v199
	v_lshlrev_b32_e32 v172, 16, v200
	v_and_b32_e32 v173, 0xffff0000, v200
	v_lshlrev_b32_e32 v162, 16, v201
	v_and_b32_e32 v163, 0xffff0000, v201
	global_load_dwordx4 v[198:201], v[222:223], off offset:256
	v_lshl_add_u64 v[222:223], v[222:223], 0, vcc
	v_pk_mul_f32 v[102:103], v[102:103], v[168:169]
	v_pk_mul_f32 v[104:105], v[104:105], v[170:171]
	v_pk_mul_f32 v[98:99], v[98:99], v[156:157]
	v_pk_mul_f32 v[100:101], v[100:101], v[158:159]
	v_pk_add_f32 v[102:103], v[102:103], v[152:153]
	v_pk_add_f32 v[104:105], v[104:105], v[160:161]
	v_pk_add_f32 v[98:99], v[98:99], v[172:173]
	v_pk_add_f32 v[100:101], v[100:101], v[162:163]
	v_pk_mul_f32 v[152:153], v[102:103], v[102:103]
	v_pk_fma_f32 v[152:153], v[104:105], v[104:105], v[152:153]
	v_pk_fma_f32 v[152:153], v[98:99], v[98:99], v[152:153]
	v_pk_fma_f32 v[152:153], v[100:101], v[100:101], v[152:153]
	v_add_f32_e32 v152, v152, v153
	v_add_f32_e32 v131, v131, v152
	v_cvt_pk_bf16_f32 v244, v102, v103
	v_cvt_pk_bf16_f32 v245, v104, v105
	v_cvt_pk_bf16_f32 v246, v98, v99
	v_cvt_pk_bf16_f32 v247, v100, v101
	global_store_dwordx4 v[154:155], v[244:247], off offset:256 sc1
	v_lshl_add_u64 v[154:155], v[154:155], 0, vcc
	s_waitcnt vmcnt(13)
	v_lshlrev_b32_e32 v152, 16, v202
	v_and_b32_e32 v153, 0xffff0000, v202
	v_lshlrev_b32_e32 v160, 16, v203
	v_and_b32_e32 v161, 0xffff0000, v203
	v_lshlrev_b32_e32 v172, 16, v204
	v_and_b32_e32 v173, 0xffff0000, v204
	v_lshlrev_b32_e32 v162, 16, v205
	v_and_b32_e32 v163, 0xffff0000, v205
	global_load_dwordx4 v[202:205], v[222:223], off
	v_pk_mul_f32 v[94:95], v[94:95], v[236:237]
	v_pk_mul_f32 v[96:97], v[96:97], v[238:239]
	v_pk_mul_f32 v[90:91], v[90:91], v[240:241]
	v_pk_mul_f32 v[92:93], v[92:93], v[242:243]
	v_pk_add_f32 v[94:95], v[94:95], v[152:153]
	v_pk_add_f32 v[96:97], v[96:97], v[160:161]
	v_pk_add_f32 v[90:91], v[90:91], v[172:173]
	v_pk_add_f32 v[92:93], v[92:93], v[162:163]
	v_pk_mul_f32 v[152:153], v[94:95], v[94:95]
	v_pk_fma_f32 v[152:153], v[96:97], v[96:97], v[152:153]
	v_pk_fma_f32 v[152:153], v[90:91], v[90:91], v[152:153]
	v_pk_fma_f32 v[152:153], v[92:93], v[92:93], v[152:153]
	v_add_f32_e32 v132, v152, v153
	v_cvt_pk_bf16_f32 v244, v94, v95
	v_cvt_pk_bf16_f32 v245, v96, v97
	v_cvt_pk_bf16_f32 v246, v90, v91
	v_cvt_pk_bf16_f32 v247, v92, v93
	global_store_dwordx4 v[154:155], v[244:247], off sc1
	s_waitcnt vmcnt(14)
	v_lshlrev_b32_e32 v152, 16, v206
	v_and_b32_e32 v153, 0xffff0000, v206
	v_lshlrev_b32_e32 v160, 16, v207
	v_and_b32_e32 v161, 0xffff0000, v207
	v_lshlrev_b32_e32 v172, 16, v208
	v_and_b32_e32 v173, 0xffff0000, v208
	v_lshlrev_b32_e32 v162, 16, v209
	v_and_b32_e32 v163, 0xffff0000, v209
	global_load_dwordx4 v[206:209], v[222:223], off offset:256
	v_lshl_add_u64 v[222:223], v[222:223], 0, vcc
	v_pk_mul_f32 v[86:87], v[86:87], v[168:169]
	v_pk_mul_f32 v[88:89], v[88:89], v[170:171]
	v_pk_mul_f32 v[82:83], v[82:83], v[156:157]
	v_pk_mul_f32 v[84:85], v[84:85], v[158:159]
	v_pk_add_f32 v[86:87], v[86:87], v[152:153]
	v_pk_add_f32 v[88:89], v[88:89], v[160:161]
	v_pk_add_f32 v[82:83], v[82:83], v[172:173]
	v_pk_add_f32 v[84:85], v[84:85], v[162:163]
	v_pk_mul_f32 v[152:153], v[86:87], v[86:87]
	v_pk_fma_f32 v[152:153], v[88:89], v[88:89], v[152:153]
	v_pk_fma_f32 v[152:153], v[82:83], v[82:83], v[152:153]
	v_pk_fma_f32 v[152:153], v[84:85], v[84:85], v[152:153]
	v_add_f32_e32 v152, v152, v153
	v_add_f32_e32 v132, v132, v152
	v_cvt_pk_bf16_f32 v244, v86, v87
	v_cvt_pk_bf16_f32 v245, v88, v89
	v_cvt_pk_bf16_f32 v246, v82, v83
	v_cvt_pk_bf16_f32 v247, v84, v85
	global_store_dwordx4 v[154:155], v[244:247], off offset:256 sc1
	v_lshl_add_u64 v[154:155], v[154:155], 0, vcc
	s_waitcnt vmcnt(15)
	v_lshlrev_b32_e32 v152, 16, v210
	v_and_b32_e32 v153, 0xffff0000, v210
	v_lshlrev_b32_e32 v160, 16, v211
	v_and_b32_e32 v161, 0xffff0000, v211
	v_lshlrev_b32_e32 v172, 16, v212
	v_and_b32_e32 v173, 0xffff0000, v212
	v_lshlrev_b32_e32 v162, 16, v213
	v_and_b32_e32 v163, 0xffff0000, v213
	v_pk_mul_f32 v[78:79], v[78:79], v[236:237]
	v_pk_mul_f32 v[80:81], v[80:81], v[238:239]
	v_pk_mul_f32 v[74:75], v[74:75], v[240:241]
	v_pk_mul_f32 v[76:77], v[76:77], v[242:243]
	v_pk_add_f32 v[78:79], v[78:79], v[152:153]
	v_pk_add_f32 v[80:81], v[80:81], v[160:161]
	v_pk_add_f32 v[74:75], v[74:75], v[172:173]
	v_pk_add_f32 v[76:77], v[76:77], v[162:163]
	v_pk_mul_f32 v[152:153], v[78:79], v[78:79]
	v_pk_fma_f32 v[152:153], v[80:81], v[80:81], v[152:153]
	v_pk_fma_f32 v[152:153], v[74:75], v[74:75], v[152:153]
	v_pk_fma_f32 v[152:153], v[76:77], v[76:77], v[152:153]
	v_add_f32_e32 v133, v152, v153
	v_cvt_pk_bf16_f32 v244, v78, v79
	v_cvt_pk_bf16_f32 v245, v80, v81
	v_cvt_pk_bf16_f32 v246, v74, v75
	v_cvt_pk_bf16_f32 v247, v76, v77
	global_store_dwordx4 v[154:155], v[244:247], off sc1
	s_waitcnt vmcnt(15)
	v_lshlrev_b32_e32 v152, 16, v214
	v_and_b32_e32 v153, 0xffff0000, v214
	v_lshlrev_b32_e32 v160, 16, v215
	v_and_b32_e32 v161, 0xffff0000, v215
	v_lshlrev_b32_e32 v172, 16, v216
	v_and_b32_e32 v173, 0xffff0000, v216
	v_lshlrev_b32_e32 v162, 16, v217
	v_and_b32_e32 v163, 0xffff0000, v217
	v_pk_mul_f32 v[70:71], v[70:71], v[168:169]
	v_pk_mul_f32 v[72:73], v[72:73], v[170:171]
	v_pk_mul_f32 v[66:67], v[66:67], v[156:157]
	v_pk_mul_f32 v[68:69], v[68:69], v[158:159]
	v_pk_add_f32 v[70:71], v[70:71], v[152:153]
	v_pk_add_f32 v[72:73], v[72:73], v[160:161]
	v_pk_add_f32 v[66:67], v[66:67], v[172:173]
	v_pk_add_f32 v[68:69], v[68:69], v[162:163]
	v_pk_mul_f32 v[152:153], v[70:71], v[70:71]
	v_pk_fma_f32 v[152:153], v[72:73], v[72:73], v[152:153]
	v_pk_fma_f32 v[152:153], v[66:67], v[66:67], v[152:153]
	v_pk_fma_f32 v[152:153], v[68:69], v[68:69], v[152:153]
	v_add_f32_e32 v152, v152, v153
	v_add_f32_e32 v133, v133, v152
	v_cvt_pk_bf16_f32 v244, v70, v71
	v_cvt_pk_bf16_f32 v245, v72, v73
	v_cvt_pk_bf16_f32 v246, v66, v67
	v_cvt_pk_bf16_f32 v247, v68, v69
	global_store_dwordx4 v[154:155], v[244:247], off offset:256 sc1
	v_lshl_add_u64 v[154:155], v[154:155], 0, vcc
	v_lshl_add_u64 v[154:155], v[154:155], 0, s[28:29]
	s_waitcnt vmcnt(15)
	v_lshlrev_b32_e32 v152, 16, v218
	v_and_b32_e32 v153, 0xffff0000, v218
	v_lshlrev_b32_e32 v160, 16, v219
	v_and_b32_e32 v161, 0xffff0000, v219
	v_lshlrev_b32_e32 v172, 16, v220
	v_and_b32_e32 v173, 0xffff0000, v220
	v_lshlrev_b32_e32 v162, 16, v221
	v_and_b32_e32 v163, 0xffff0000, v221
	v_pk_mul_f32 v[62:63], v[62:63], v[236:237]
	v_pk_mul_f32 v[64:65], v[64:65], v[238:239]
	v_pk_mul_f32 v[58:59], v[58:59], v[240:241]
	v_pk_mul_f32 v[60:61], v[60:61], v[242:243]
	v_pk_add_f32 v[62:63], v[62:63], v[152:153]
	v_pk_add_f32 v[64:65], v[64:65], v[160:161]
	v_pk_add_f32 v[58:59], v[58:59], v[172:173]
	v_pk_add_f32 v[60:61], v[60:61], v[162:163]
	v_pk_mul_f32 v[152:153], v[62:63], v[62:63]
	v_pk_fma_f32 v[152:153], v[64:65], v[64:65], v[152:153]
	v_pk_fma_f32 v[152:153], v[58:59], v[58:59], v[152:153]
	v_pk_fma_f32 v[152:153], v[60:61], v[60:61], v[152:153]
	v_add_f32_e32 v134, v152, v153
	v_cvt_pk_bf16_f32 v244, v62, v63
	v_cvt_pk_bf16_f32 v245, v64, v65
	v_cvt_pk_bf16_f32 v246, v58, v59
	v_cvt_pk_bf16_f32 v247, v60, v61
	global_store_dwordx4 v[154:155], v[244:247], off sc1
	s_waitcnt vmcnt(15)
	v_lshlrev_b32_e32 v152, 16, v164
	v_and_b32_e32 v153, 0xffff0000, v164
	v_lshlrev_b32_e32 v160, 16, v165
	v_and_b32_e32 v161, 0xffff0000, v165
	v_lshlrev_b32_e32 v172, 16, v166
	v_and_b32_e32 v173, 0xffff0000, v166
	v_lshlrev_b32_e32 v162, 16, v167
	v_and_b32_e32 v163, 0xffff0000, v167
	v_pk_mul_f32 v[54:55], v[54:55], v[168:169]
	v_pk_mul_f32 v[56:57], v[56:57], v[170:171]
	v_pk_mul_f32 v[50:51], v[50:51], v[156:157]
	v_pk_mul_f32 v[52:53], v[52:53], v[158:159]
	v_pk_add_f32 v[54:55], v[54:55], v[152:153]
	v_pk_add_f32 v[56:57], v[56:57], v[160:161]
	v_pk_add_f32 v[50:51], v[50:51], v[172:173]
	v_pk_add_f32 v[52:53], v[52:53], v[162:163]
	v_pk_mul_f32 v[152:153], v[54:55], v[54:55]
	v_pk_fma_f32 v[152:153], v[56:57], v[56:57], v[152:153]
	v_pk_fma_f32 v[152:153], v[50:51], v[50:51], v[152:153]
	v_pk_fma_f32 v[152:153], v[52:53], v[52:53], v[152:153]
	v_add_f32_e32 v152, v152, v153
	v_add_f32_e32 v134, v134, v152
	v_cvt_pk_bf16_f32 v244, v54, v55
	v_cvt_pk_bf16_f32 v245, v56, v57
	v_cvt_pk_bf16_f32 v246, v50, v51
	v_cvt_pk_bf16_f32 v247, v52, v53
	global_store_dwordx4 v[154:155], v[244:247], off offset:256 sc1
	v_lshl_add_u64 v[154:155], v[154:155], 0, vcc
	s_waitcnt vmcnt(15)
	v_lshlrev_b32_e32 v152, 16, v186
	v_and_b32_e32 v153, 0xffff0000, v186
	v_lshlrev_b32_e32 v160, 16, v187
	v_and_b32_e32 v161, 0xffff0000, v187
	v_lshlrev_b32_e32 v172, 16, v188
	v_and_b32_e32 v173, 0xffff0000, v188
	v_lshlrev_b32_e32 v162, 16, v189
	v_and_b32_e32 v163, 0xffff0000, v189
	v_pk_mul_f32 v[46:47], v[46:47], v[236:237]
	v_pk_mul_f32 v[48:49], v[48:49], v[238:239]
	v_pk_mul_f32 v[42:43], v[42:43], v[240:241]
	v_pk_mul_f32 v[44:45], v[44:45], v[242:243]
	v_pk_add_f32 v[46:47], v[46:47], v[152:153]
	v_pk_add_f32 v[48:49], v[48:49], v[160:161]
	v_pk_add_f32 v[42:43], v[42:43], v[172:173]
	v_pk_add_f32 v[44:45], v[44:45], v[162:163]
	v_pk_mul_f32 v[152:153], v[46:47], v[46:47]
	v_pk_fma_f32 v[152:153], v[48:49], v[48:49], v[152:153]
	v_pk_fma_f32 v[152:153], v[42:43], v[42:43], v[152:153]
	v_pk_fma_f32 v[152:153], v[44:45], v[44:45], v[152:153]
	v_add_f32_e32 v135, v152, v153
	v_cvt_pk_bf16_f32 v244, v46, v47
	v_cvt_pk_bf16_f32 v245, v48, v49
	v_cvt_pk_bf16_f32 v246, v42, v43
	v_cvt_pk_bf16_f32 v247, v44, v45
	global_store_dwordx4 v[154:155], v[244:247], off sc1
	s_waitcnt vmcnt(14)
	v_lshlrev_b32_e32 v152, 16, v190
	v_and_b32_e32 v153, 0xffff0000, v190
	v_lshlrev_b32_e32 v160, 16, v191
	v_and_b32_e32 v161, 0xffff0000, v191
	v_lshlrev_b32_e32 v172, 16, v192
	v_and_b32_e32 v173, 0xffff0000, v192
	v_lshlrev_b32_e32 v162, 16, v193
	v_and_b32_e32 v163, 0xffff0000, v193
	v_pk_mul_f32 v[38:39], v[38:39], v[168:169]
	v_pk_mul_f32 v[40:41], v[40:41], v[170:171]
	v_pk_mul_f32 v[34:35], v[34:35], v[156:157]
	v_pk_mul_f32 v[36:37], v[36:37], v[158:159]
	v_pk_add_f32 v[38:39], v[38:39], v[152:153]
	v_pk_add_f32 v[40:41], v[40:41], v[160:161]
	v_pk_add_f32 v[34:35], v[34:35], v[172:173]
	v_pk_add_f32 v[36:37], v[36:37], v[162:163]
	v_pk_mul_f32 v[152:153], v[38:39], v[38:39]
	v_pk_fma_f32 v[152:153], v[40:41], v[40:41], v[152:153]
	v_pk_fma_f32 v[152:153], v[34:35], v[34:35], v[152:153]
	v_pk_fma_f32 v[152:153], v[36:37], v[36:37], v[152:153]
	v_add_f32_e32 v152, v152, v153
	v_add_f32_e32 v135, v135, v152
	v_cvt_pk_bf16_f32 v244, v38, v39
	v_cvt_pk_bf16_f32 v245, v40, v41
	v_cvt_pk_bf16_f32 v246, v34, v35
	v_cvt_pk_bf16_f32 v247, v36, v37
	global_store_dwordx4 v[154:155], v[244:247], off offset:256 sc1
	v_lshl_add_u64 v[154:155], v[154:155], 0, vcc
	s_waitcnt vmcnt(13)
	v_lshlrev_b32_e32 v152, 16, v194
	v_and_b32_e32 v153, 0xffff0000, v194
	v_lshlrev_b32_e32 v160, 16, v195
	v_and_b32_e32 v161, 0xffff0000, v195
	v_lshlrev_b32_e32 v172, 16, v196
	v_and_b32_e32 v173, 0xffff0000, v196
	v_lshlrev_b32_e32 v162, 16, v197
	v_and_b32_e32 v163, 0xffff0000, v197
	v_pk_mul_f32 v[30:31], v[30:31], v[236:237]
	v_pk_mul_f32 v[32:33], v[32:33], v[238:239]
	v_pk_mul_f32 v[26:27], v[26:27], v[240:241]
	v_pk_mul_f32 v[28:29], v[28:29], v[242:243]
	v_pk_add_f32 v[30:31], v[30:31], v[152:153]
	v_pk_add_f32 v[32:33], v[32:33], v[160:161]
	v_pk_add_f32 v[26:27], v[26:27], v[172:173]
	v_pk_add_f32 v[28:29], v[28:29], v[162:163]
	v_pk_mul_f32 v[152:153], v[30:31], v[30:31]
	v_pk_fma_f32 v[152:153], v[32:33], v[32:33], v[152:153]
	v_pk_fma_f32 v[152:153], v[26:27], v[26:27], v[152:153]
	v_pk_fma_f32 v[152:153], v[28:29], v[28:29], v[152:153]
	v_add_f32_e32 v136, v152, v153
	v_cvt_pk_bf16_f32 v244, v30, v31
	v_cvt_pk_bf16_f32 v245, v32, v33
	v_cvt_pk_bf16_f32 v246, v26, v27
	v_cvt_pk_bf16_f32 v247, v28, v29
	global_store_dwordx4 v[154:155], v[244:247], off sc1
	s_waitcnt vmcnt(12)
	v_lshlrev_b32_e32 v152, 16, v198
	v_and_b32_e32 v153, 0xffff0000, v198
	v_lshlrev_b32_e32 v160, 16, v199
	v_and_b32_e32 v161, 0xffff0000, v199
	v_lshlrev_b32_e32 v172, 16, v200
	v_and_b32_e32 v173, 0xffff0000, v200
	v_lshlrev_b32_e32 v162, 16, v201
	v_and_b32_e32 v163, 0xffff0000, v201
	v_pk_mul_f32 v[22:23], v[22:23], v[168:169]
	v_pk_mul_f32 v[24:25], v[24:25], v[170:171]
	v_pk_mul_f32 v[18:19], v[18:19], v[156:157]
	v_pk_mul_f32 v[20:21], v[20:21], v[158:159]
	v_pk_add_f32 v[22:23], v[22:23], v[152:153]
	v_pk_add_f32 v[24:25], v[24:25], v[160:161]
	v_pk_add_f32 v[18:19], v[18:19], v[172:173]
	v_pk_add_f32 v[20:21], v[20:21], v[162:163]
	v_pk_mul_f32 v[152:153], v[22:23], v[22:23]
	v_pk_fma_f32 v[152:153], v[24:25], v[24:25], v[152:153]
	v_pk_fma_f32 v[152:153], v[18:19], v[18:19], v[152:153]
	v_pk_fma_f32 v[152:153], v[20:21], v[20:21], v[152:153]
	v_add_f32_e32 v152, v152, v153
	v_add_f32_e32 v136, v136, v152
	v_cvt_pk_bf16_f32 v244, v22, v23
	v_cvt_pk_bf16_f32 v245, v24, v25
	v_cvt_pk_bf16_f32 v246, v18, v19
	v_cvt_pk_bf16_f32 v247, v20, v21
	global_store_dwordx4 v[154:155], v[244:247], off offset:256 sc1
	v_lshl_add_u64 v[154:155], v[154:155], 0, vcc
	s_waitcnt vmcnt(11)
	v_lshlrev_b32_e32 v152, 16, v202
	v_and_b32_e32 v153, 0xffff0000, v202
	v_lshlrev_b32_e32 v160, 16, v203
	v_and_b32_e32 v161, 0xffff0000, v203
	v_lshlrev_b32_e32 v172, 16, v204
	v_and_b32_e32 v173, 0xffff0000, v204
	v_lshlrev_b32_e32 v162, 16, v205
	v_and_b32_e32 v163, 0xffff0000, v205
	v_pk_mul_f32 v[14:15], v[14:15], v[236:237]
	v_pk_mul_f32 v[16:17], v[16:17], v[238:239]
	v_pk_mul_f32 v[10:11], v[10:11], v[240:241]
	v_pk_mul_f32 v[12:13], v[12:13], v[242:243]
	v_pk_add_f32 v[14:15], v[14:15], v[152:153]
	v_pk_add_f32 v[16:17], v[16:17], v[160:161]
	v_pk_add_f32 v[10:11], v[10:11], v[172:173]
	v_pk_add_f32 v[12:13], v[12:13], v[162:163]
	v_pk_mul_f32 v[152:153], v[14:15], v[14:15]
	v_pk_fma_f32 v[152:153], v[16:17], v[16:17], v[152:153]
	v_pk_fma_f32 v[152:153], v[10:11], v[10:11], v[152:153]
	v_pk_fma_f32 v[152:153], v[12:13], v[12:13], v[152:153]
	v_add_f32_e32 v137, v152, v153
	v_cvt_pk_bf16_f32 v244, v14, v15
	v_cvt_pk_bf16_f32 v245, v16, v17
	v_cvt_pk_bf16_f32 v246, v10, v11
	v_cvt_pk_bf16_f32 v247, v12, v13
	global_store_dwordx4 v[154:155], v[244:247], off sc1
	s_waitcnt vmcnt(10)
	v_lshlrev_b32_e32 v152, 16, v206
	v_and_b32_e32 v153, 0xffff0000, v206
	v_lshlrev_b32_e32 v160, 16, v207
	v_and_b32_e32 v161, 0xffff0000, v207
	v_lshlrev_b32_e32 v172, 16, v208
	v_and_b32_e32 v173, 0xffff0000, v208
	v_lshlrev_b32_e32 v162, 16, v209
	v_and_b32_e32 v163, 0xffff0000, v209
	v_pk_mul_f32 v[6:7], v[6:7], v[168:169]
	v_pk_mul_f32 v[8:9], v[8:9], v[170:171]
	v_pk_mul_f32 v[2:3], v[2:3], v[156:157]
	v_pk_mul_f32 v[4:5], v[4:5], v[158:159]
	v_pk_add_f32 v[6:7], v[6:7], v[152:153]
	v_pk_add_f32 v[8:9], v[8:9], v[160:161]
	v_pk_add_f32 v[2:3], v[2:3], v[172:173]
	v_pk_add_f32 v[4:5], v[4:5], v[162:163]
	v_pk_mul_f32 v[152:153], v[6:7], v[6:7]
	v_pk_fma_f32 v[152:153], v[8:9], v[8:9], v[152:153]
	v_pk_fma_f32 v[152:153], v[2:3], v[2:3], v[152:153]
	v_pk_fma_f32 v[152:153], v[4:5], v[4:5], v[152:153]
	v_add_f32_e32 v152, v152, v153
	v_add_f32_e32 v137, v137, v152
	v_cvt_pk_bf16_f32 v244, v6, v7
	v_cvt_pk_bf16_f32 v245, v8, v9
	v_cvt_pk_bf16_f32 v246, v2, v3
	v_cvt_pk_bf16_f32 v247, v4, v5
	global_store_dwordx4 v[154:155], v[244:247], off offset:256 sc1
	v_lshl_add_u64 v[154:155], v[154:155], 0, vcc
	v_mov_b32_e32 v206, v145
	v_mov_b32_e32 v207, v185
	s_waitcnt lgkmcnt(0)
	v_lshrrev_b32_e32 v145, 4, v224
	v_and_b32_e32 v145, 15, v145
	v_lshlrev_b32_e32 v145, 2, v145
	v_lshl_add_u32 v145, v174, 6, v145
	v_add_u32_e32 v145, 0xc000, v145
	ds_write_b32 v145, v130
	ds_write_b32 v145, v131 offset:1024
	ds_write_b32 v145, v132 offset:2048
	ds_write_b32 v145, v133 offset:3072
	ds_write_b32 v145, v134 offset:8192
	ds_write_b32 v145, v135 offset:9216
	ds_write_b32 v145, v136 offset:10240
	ds_write_b32 v145, v137 offset:11264
	s_waitcnt lgkmcnt(0)
	s_barrier
	v_cmp_gt_u32_e32 vcc, 0x100, v224
	s_and_saveexec_b64 s[30:31], vcc
	s_cbranch_execz .Lrf_x1_a
	v_lshlrev_b32_e32 v145, 6, v224
	v_add_u32_e32 v145, 0xc000, v145
	ds_read_b128 v[186:189], v145
	ds_read_b128 v[190:193], v145 offset:16
	ds_read_b128 v[194:197], v145 offset:32
	ds_read_b128 v[198:201], v145 offset:48
	s_lshl_b32 s13, s43, 2
	s_add_i32 s13, s13, s58
	s_lshl_b32 s13, s13, 10
	s_add_u32 s28, s40, 0x80000
	s_addc_u32 s29, s41, 0
	s_add_u32 s28, s28, s13
	s_addc_u32 s29, s29, 0
	v_lshlrev_b32_e32 v202, 2, v224
	s_waitcnt lgkmcnt(0)
	v_add_f32_e32 v186, v186, v187
	v_add_f32_e32 v188, v188, v189
	v_add_f32_e32 v186, v186, v188
	v_add_f32_e32 v190, v190, v191
	v_add_f32_e32 v192, v192, v193
	v_add_f32_e32 v190, v190, v192
	v_add_f32_e32 v194, v194, v195
	v_add_f32_e32 v196, v196, v197
	v_add_f32_e32 v194, v194, v196
	v_add_f32_e32 v198, v198, v199
	v_add_f32_e32 v200, v200, v201
	v_add_f32_e32 v198, v198, v200
	v_add_f32_e32 v186, v186, v190
	v_add_f32_e32 v194, v194, v198
	v_add_f32_e32 v186, v186, v194
	global_store_dword v202, v186, s[28:29] sc1
.Lrf_x1_a:
	s_or_b64 exec, exec, s[30:31]
	s_waitcnt vmcnt(0)
	s_barrier
	v_cmp_eq_u32_e32 vcc, 0, v224
	s_and_saveexec_b64 s[30:31], vcc
	s_cbranch_execz .Lrf_x2_a
	s_lshl_b32 s13, s43, 2
	s_add_u32 s28, s40, 0x70000
	s_addc_u32 s29, s41, 0
	s_add_u32 s28, s28, s13
	s_addc_u32 s29, s29, 0
	v_mov_b32_e32 v202, 1
	global_atomic_add v1, v202, s[28:29]
	s_mov_b32 s13, 0
.Lrf_spin_a:
	global_load_dword v202, v1, s[28:29] sc1
	s_waitcnt vmcnt(0)
	v_readfirstlane_b32 s23, v202
	s_cmp_ge_u32 s23, 4
	s_cbranch_scc1 .Lrf_x2_a
	s_add_i32 s13, s13, 1
	s_cmp_lt_u32 s13, 0x1000
	s_cbranch_scc1 .Lrf_spin_a
.Lrf_x2_a:
	s_or_b64 exec, exec, s[30:31]
	s_barrier
	v_cmp_gt_u32_e32 vcc, 0x100, v224
	s_and_saveexec_b64 s[30:31], vcc
	s_cbranch_execz .Lrf_x3_a
	s_lshl_b32 s13, s43, 12
	s_add_u32 s28, s40, 0x80000
	s_addc_u32 s29, s41, 0
	s_add_u32 s28, s28, s13
	s_addc_u32 s29, s29, 0
	v_lshlrev_b32_e32 v202, 2, v224
	global_load_dword v186, v202, s[28:29] sc1
	global_load_dword v187, v202, s[28:29] offset:1024 sc1
	global_load_dword v188, v202, s[28:29] offset:2048 sc1
	global_load_dword v189, v202, s[28:29] offset:3072 sc1
	v_mov_b32_e32 v203, 0x3a800000
	v_mov_b32_e32 v204, 0x358637bd
	s_waitcnt vmcnt(0)
	v_add_f32_e32 v186, v186, v187
	v_add_f32_e32 v188, v188, v189
	v_add_f32_e32 v186, v186, v188
	v_fma_f32 v186, v186, v203, v204
	v_rsq_f32_e32 v186, v186
	v_add_u32_e32 v202, 0xc000, v202
	s_nop 0
	ds_write_b32 v202, v186
.Lrf_x3_a:
	s_or_b64 exec, exec, s[30:31]
	s_waitcnt lgkmcnt(0)
	s_barrier
	v_lshlrev_b32_e32 v145, 2, v174
	v_add_u32_e32 v145, 0xc000, v145
	ds_read_b32 v130, v145
	ds_read_b32 v131, v145 offset:64
	ds_read_b32 v132, v145 offset:128
	ds_read_b32 v133, v145 offset:192
	ds_read_b32 v134, v145 offset:512
	ds_read_b32 v135, v145 offset:576
	ds_read_b32 v136, v145 offset:640
	ds_read_b32 v137, v145 offset:704
	s_load_dwordx2 s[28:29], s[0:1], 0x78
	v_lshl_or_b32 v202, s58, 8, v183
	v_lshlrev_b32_e32 v202, 2, v202
	v_mov_b32_e32 v203, 0
	s_lshr_b32 s13, s43, 4
	s_mul_i32 s13, s13, 0x9000
	s_add_u32 s30, s40, 0x33000
	s_addc_u32 s31, s41, 0
	s_add_u32 s30, s30, s13
	s_addc_u32 s31, s31, 0
	v_lshl_add_u64 v[208:209], s[30:31], 0, v[202:203]
	s_waitcnt lgkmcnt(0)
	s_add_u32 s28, s28, 0x1000
	s_addc_u32 s29, s29, 0
	v_lshl_add_u64 v[204:205], s[28:29], 0, v[202:203]
	global_load_dwordx4 v[186:189], v[204:205], off
	global_load_dwordx4 v[190:193], v[204:205], off offset:16
	global_load_dwordx4 v[194:197], v[204:205], off offset:512
	global_load_dwordx4 v[198:201], v[204:205], off offset:528
	s_mov_b64 vcc, 0x1000
	v_lshl_add_u64 v[222:223], v[208:209], 0, vcc
	global_load_dwordx4 v[210:213], v[222:223], off
	global_load_dwordx4 v[214:217], v[222:223], off offset:16
	global_load_dwordx4 v[218:221], v[222:223], off offset:512
	global_load_dwordx4 v[164:167], v[222:223], off offset:528
	global_load_dwordx4 v[236:239], v[208:209], off
	global_load_dwordx4 v[240:243], v[208:209], off offset:16
	global_load_dwordx4 v[168:171], v[208:209], off offset:512
	global_load_dwordx4 v[156:159], v[208:209], off offset:528
	s_add_u32 s28, s40, 0x9000000
	s_addc_u32 s29, s41, 0
	v_lshl_add_u64 v[154:155], v[206:207], 1, s[28:29]
	s_mov_b64 vcc, 0x8000
	s_mov_b64 s[28:29], 0x20000
	s_waitcnt vmcnt(0) lgkmcnt(0)
	v_pk_add_f32 v[210:211], v[210:211], 1.0 op_sel_hi:[1,0]
	v_pk_mul_f32 v[186:187], v[186:187], v[210:211]
	v_pk_add_f32 v[212:213], v[212:213], 1.0 op_sel_hi:[1,0]
	v_pk_mul_f32 v[188:189], v[188:189], v[212:213]
	v_pk_add_f32 v[214:215], v[214:215], 1.0 op_sel_hi:[1,0]
	v_pk_mul_f32 v[190:191], v[190:191], v[214:215]
	v_pk_add_f32 v[216:217], v[216:217], 1.0 op_sel_hi:[1,0]
	v_pk_mul_f32 v[192:193], v[192:193], v[216:217]
	v_pk_add_f32 v[218:219], v[218:219], 1.0 op_sel_hi:[1,0]
	v_pk_mul_f32 v[194:195], v[194:195], v[218:219]
	v_pk_add_f32 v[220:221], v[220:221], 1.0 op_sel_hi:[1,0]
	v_pk_mul_f32 v[196:197], v[196:197], v[220:221]
	v_pk_add_f32 v[164:165], v[164:165], 1.0 op_sel_hi:[1,0]
	v_pk_mul_f32 v[198:199], v[198:199], v[164:165]
	v_pk_add_f32 v[166:167], v[166:167], 1.0 op_sel_hi:[1,0]
	v_pk_mul_f32 v[200:201], v[200:201], v[166:167]
	v_mul_f32_e32 v126, v130, v126
	v_mul_f32_e32 v127, v130, v127
	v_mul_f32_e32 v128, v130, v128
	v_mul_f32_e32 v129, v130, v129
	v_mul_f32_e32 v122, v130, v122
	v_mul_f32_e32 v123, v130, v123
	v_mul_f32_e32 v124, v130, v124
	v_mul_f32_e32 v125, v130, v125
	v_pk_fma_f32 v[126:127], v[126:127], v[186:187], v[236:237]
	v_pk_fma_f32 v[128:129], v[128:129], v[188:189], v[238:239]
	v_pk_fma_f32 v[122:123], v[122:123], v[190:191], v[240:241]
	v_pk_fma_f32 v[124:125], v[124:125], v[192:193], v[242:243]
	v_cvt_pk_bf16_f32 v126, v126, v127
	v_cvt_pk_bf16_f32 v127, v128, v129
	v_cvt_pk_bf16_f32 v128, v122, v123
	v_cvt_pk_bf16_f32 v129, v124, v125
	global_store_dwordx4 v[154:155], v[126:129], off sc1
	v_mul_f32_e32 v118, v130, v118
	v_mul_f32_e32 v119, v130, v119
	v_mul_f32_e32 v120, v130, v120
	v_mul_f32_e32 v121, v130, v121
	v_mul_f32_e32 v114, v130, v114
	v_mul_f32_e32 v115, v130, v115
	v_mul_f32_e32 v116, v130, v116
	v_mul_f32_e32 v117, v130, v117
	v_pk_fma_f32 v[118:119], v[118:119], v[194:195], v[168:169]
	v_pk_fma_f32 v[120:121], v[120:121], v[196:197], v[170:171]
	v_pk_fma_f32 v[114:115], v[114:115], v[198:199], v[156:157]
	v_pk_fma_f32 v[116:117], v[116:117], v[200:201], v[158:159]
	v_cvt_pk_bf16_f32 v118, v118, v119
	v_cvt_pk_bf16_f32 v119, v120, v121
	v_cvt_pk_bf16_f32 v120, v114, v115
	v_cvt_pk_bf16_f32 v121, v116, v117
	global_store_dwordx4 v[154:155], v[118:121], off offset:256 sc1
	v_lshl_add_u64 v[154:155], v[154:155], 0, vcc
	v_mul_f32_e32 v110, v131, v110
	v_mul_f32_e32 v111, v131, v111
	v_mul_f32_e32 v112, v131, v112
	v_mul_f32_e32 v113, v131, v113
	v_mul_f32_e32 v106, v131, v106
	v_mul_f32_e32 v107, v131, v107
	v_mul_f32_e32 v108, v131, v108
	v_mul_f32_e32 v109, v131, v109
	v_pk_fma_f32 v[110:111], v[110:111], v[186:187], v[236:237]
	v_pk_fma_f32 v[112:113], v[112:113], v[188:189], v[238:239]
	v_pk_fma_f32 v[106:107], v[106:107], v[190:191], v[240:241]
	v_pk_fma_f32 v[108:109], v[108:109], v[192:193], v[242:243]
	v_cvt_pk_bf16_f32 v110, v110, v111
	v_cvt_pk_bf16_f32 v111, v112, v113
	v_cvt_pk_bf16_f32 v112, v106, v107
	v_cvt_pk_bf16_f32 v113, v108, v109
	global_store_dwordx4 v[154:155], v[110:113], off sc1
	v_mul_f32_e32 v102, v131, v102
	v_mul_f32_e32 v103, v131, v103
	v_mul_f32_e32 v104, v131, v104
	v_mul_f32_e32 v105, v131, v105
	v_mul_f32_e32 v98, v131, v98
	v_mul_f32_e32 v99, v131, v99
	v_mul_f32_e32 v100, v131, v100
	v_mul_f32_e32 v101, v131, v101
	v_pk_fma_f32 v[102:103], v[102:103], v[194:195], v[168:169]
	v_pk_fma_f32 v[104:105], v[104:105], v[196:197], v[170:171]
	v_pk_fma_f32 v[98:99], v[98:99], v[198:199], v[156:157]
	v_pk_fma_f32 v[100:101], v[100:101], v[200:201], v[158:159]
	v_cvt_pk_bf16_f32 v102, v102, v103
	v_cvt_pk_bf16_f32 v103, v104, v105
	v_cvt_pk_bf16_f32 v104, v98, v99
	v_cvt_pk_bf16_f32 v105, v100, v101
	global_store_dwordx4 v[154:155], v[102:105], off offset:256 sc1
	v_lshl_add_u64 v[154:155], v[154:155], 0, vcc
	v_mul_f32_e32 v94, v132, v94
	v_mul_f32_e32 v95, v132, v95
	v_mul_f32_e32 v96, v132, v96
	v_mul_f32_e32 v97, v132, v97
	v_mul_f32_e32 v90, v132, v90
	v_mul_f32_e32 v91, v132, v91
	v_mul_f32_e32 v92, v132, v92
	v_mul_f32_e32 v93, v132, v93
	v_pk_fma_f32 v[94:95], v[94:95], v[186:187], v[236:237]
	v_pk_fma_f32 v[96:97], v[96:97], v[188:189], v[238:239]
	v_pk_fma_f32 v[90:91], v[90:91], v[190:191], v[240:241]
	v_pk_fma_f32 v[92:93], v[92:93], v[192:193], v[242:243]
	v_cvt_pk_bf16_f32 v94, v94, v95
	v_cvt_pk_bf16_f32 v95, v96, v97
	v_cvt_pk_bf16_f32 v96, v90, v91
	v_cvt_pk_bf16_f32 v97, v92, v93
	global_store_dwordx4 v[154:155], v[94:97], off sc1
	v_mul_f32_e32 v86, v132, v86
	v_mul_f32_e32 v87, v132, v87
	v_mul_f32_e32 v88, v132, v88
	v_mul_f32_e32 v89, v132, v89
	v_mul_f32_e32 v82, v132, v82
	v_mul_f32_e32 v83, v132, v83
	v_mul_f32_e32 v84, v132, v84
	v_mul_f32_e32 v85, v132, v85
	v_pk_fma_f32 v[86:87], v[86:87], v[194:195], v[168:169]
	v_pk_fma_f32 v[88:89], v[88:89], v[196:197], v[170:171]
	v_pk_fma_f32 v[82:83], v[82:83], v[198:199], v[156:157]
	v_pk_fma_f32 v[84:85], v[84:85], v[200:201], v[158:159]
	v_cvt_pk_bf16_f32 v86, v86, v87
	v_cvt_pk_bf16_f32 v87, v88, v89
	v_cvt_pk_bf16_f32 v88, v82, v83
	v_cvt_pk_bf16_f32 v89, v84, v85
	global_store_dwordx4 v[154:155], v[86:89], off offset:256 sc1
	v_lshl_add_u64 v[154:155], v[154:155], 0, vcc
	v_mul_f32_e32 v78, v133, v78
	v_mul_f32_e32 v79, v133, v79
	v_mul_f32_e32 v80, v133, v80
	v_mul_f32_e32 v81, v133, v81
	v_mul_f32_e32 v74, v133, v74
	v_mul_f32_e32 v75, v133, v75
	v_mul_f32_e32 v76, v133, v76
	v_mul_f32_e32 v77, v133, v77
	v_pk_fma_f32 v[78:79], v[78:79], v[186:187], v[236:237]
	v_pk_fma_f32 v[80:81], v[80:81], v[188:189], v[238:239]
	v_pk_fma_f32 v[74:75], v[74:75], v[190:191], v[240:241]
	v_pk_fma_f32 v[76:77], v[76:77], v[192:193], v[242:243]
	v_cvt_pk_bf16_f32 v78, v78, v79
	v_cvt_pk_bf16_f32 v79, v80, v81
	v_cvt_pk_bf16_f32 v80, v74, v75
	v_cvt_pk_bf16_f32 v81, v76, v77
	global_store_dwordx4 v[154:155], v[78:81], off sc1
	v_mul_f32_e32 v70, v133, v70
	v_mul_f32_e32 v71, v133, v71
	v_mul_f32_e32 v72, v133, v72
	v_mul_f32_e32 v73, v133, v73
	v_mul_f32_e32 v66, v133, v66
	v_mul_f32_e32 v67, v133, v67
	v_mul_f32_e32 v68, v133, v68
	v_mul_f32_e32 v69, v133, v69
	v_pk_fma_f32 v[70:71], v[70:71], v[194:195], v[168:169]
	v_pk_fma_f32 v[72:73], v[72:73], v[196:197], v[170:171]
	v_pk_fma_f32 v[66:67], v[66:67], v[198:199], v[156:157]
	v_pk_fma_f32 v[68:69], v[68:69], v[200:201], v[158:159]
	v_cvt_pk_bf16_f32 v70, v70, v71
	v_cvt_pk_bf16_f32 v71, v72, v73
	v_cvt_pk_bf16_f32 v72, v66, v67
	v_cvt_pk_bf16_f32 v73, v68, v69
	global_store_dwordx4 v[154:155], v[70:73], off offset:256 sc1
	v_lshl_add_u64 v[154:155], v[154:155], 0, vcc
	v_lshl_add_u64 v[154:155], v[154:155], 0, s[28:29]
	v_mul_f32_e32 v62, v134, v62
	v_mul_f32_e32 v63, v134, v63
	v_mul_f32_e32 v64, v134, v64
	v_mul_f32_e32 v65, v134, v65
	v_mul_f32_e32 v58, v134, v58
	v_mul_f32_e32 v59, v134, v59
	v_mul_f32_e32 v60, v134, v60
	v_mul_f32_e32 v61, v134, v61
	v_pk_fma_f32 v[62:63], v[62:63], v[186:187], v[236:237]
	v_pk_fma_f32 v[64:65], v[64:65], v[188:189], v[238:239]
	v_pk_fma_f32 v[58:59], v[58:59], v[190:191], v[240:241]
	v_pk_fma_f32 v[60:61], v[60:61], v[192:193], v[242:243]
	v_cvt_pk_bf16_f32 v62, v62, v63
	v_cvt_pk_bf16_f32 v63, v64, v65
	v_cvt_pk_bf16_f32 v64, v58, v59
	v_cvt_pk_bf16_f32 v65, v60, v61
	global_store_dwordx4 v[154:155], v[62:65], off sc1
	v_mul_f32_e32 v54, v134, v54
	v_mul_f32_e32 v55, v134, v55
	v_mul_f32_e32 v56, v134, v56
	v_mul_f32_e32 v57, v134, v57
	v_mul_f32_e32 v50, v134, v50
	v_mul_f32_e32 v51, v134, v51
	v_mul_f32_e32 v52, v134, v52
	v_mul_f32_e32 v53, v134, v53
	v_pk_fma_f32 v[54:55], v[54:55], v[194:195], v[168:169]
	v_pk_fma_f32 v[56:57], v[56:57], v[196:197], v[170:171]
	v_pk_fma_f32 v[50:51], v[50:51], v[198:199], v[156:157]
	v_pk_fma_f32 v[52:53], v[52:53], v[200:201], v[158:159]
	v_cvt_pk_bf16_f32 v54, v54, v55
	v_cvt_pk_bf16_f32 v55, v56, v57
	v_cvt_pk_bf16_f32 v56, v50, v51
	v_cvt_pk_bf16_f32 v57, v52, v53
	global_store_dwordx4 v[154:155], v[54:57], off offset:256 sc1
	v_lshl_add_u64 v[154:155], v[154:155], 0, vcc
	v_mul_f32_e32 v46, v135, v46
	v_mul_f32_e32 v47, v135, v47
	v_mul_f32_e32 v48, v135, v48
	v_mul_f32_e32 v49, v135, v49
	v_mul_f32_e32 v42, v135, v42
	v_mul_f32_e32 v43, v135, v43
	v_mul_f32_e32 v44, v135, v44
	v_mul_f32_e32 v45, v135, v45
	v_pk_fma_f32 v[46:47], v[46:47], v[186:187], v[236:237]
	v_pk_fma_f32 v[48:49], v[48:49], v[188:189], v[238:239]
	v_pk_fma_f32 v[42:43], v[42:43], v[190:191], v[240:241]
	v_pk_fma_f32 v[44:45], v[44:45], v[192:193], v[242:243]
	v_cvt_pk_bf16_f32 v46, v46, v47
	v_cvt_pk_bf16_f32 v47, v48, v49
	v_cvt_pk_bf16_f32 v48, v42, v43
	v_cvt_pk_bf16_f32 v49, v44, v45
	global_store_dwordx4 v[154:155], v[46:49], off sc1
	v_mul_f32_e32 v38, v135, v38
	v_mul_f32_e32 v39, v135, v39
	v_mul_f32_e32 v40, v135, v40
	v_mul_f32_e32 v41, v135, v41
	v_mul_f32_e32 v34, v135, v34
	v_mul_f32_e32 v35, v135, v35
	v_mul_f32_e32 v36, v135, v36
	v_mul_f32_e32 v37, v135, v37
	v_pk_fma_f32 v[38:39], v[38:39], v[194:195], v[168:169]
	v_pk_fma_f32 v[40:41], v[40:41], v[196:197], v[170:171]
	v_pk_fma_f32 v[34:35], v[34:35], v[198:199], v[156:157]
	v_pk_fma_f32 v[36:37], v[36:37], v[200:201], v[158:159]
	v_cvt_pk_bf16_f32 v38, v38, v39
	v_cvt_pk_bf16_f32 v39, v40, v41
	v_cvt_pk_bf16_f32 v40, v34, v35
	v_cvt_pk_bf16_f32 v41, v36, v37
	global_store_dwordx4 v[154:155], v[38:41], off offset:256 sc1
	v_lshl_add_u64 v[154:155], v[154:155], 0, vcc
	v_mul_f32_e32 v30, v136, v30
	v_mul_f32_e32 v31, v136, v31
	v_mul_f32_e32 v32, v136, v32
	v_mul_f32_e32 v33, v136, v33
	v_mul_f32_e32 v26, v136, v26
	v_mul_f32_e32 v27, v136, v27
	v_mul_f32_e32 v28, v136, v28
	v_mul_f32_e32 v29, v136, v29
	v_pk_fma_f32 v[30:31], v[30:31], v[186:187], v[236:237]
	v_pk_fma_f32 v[32:33], v[32:33], v[188:189], v[238:239]
	v_pk_fma_f32 v[26:27], v[26:27], v[190:191], v[240:241]
	v_pk_fma_f32 v[28:29], v[28:29], v[192:193], v[242:243]
	v_cvt_pk_bf16_f32 v30, v30, v31
	v_cvt_pk_bf16_f32 v31, v32, v33
	v_cvt_pk_bf16_f32 v32, v26, v27
	v_cvt_pk_bf16_f32 v33, v28, v29
	global_store_dwordx4 v[154:155], v[30:33], off sc1
	v_mul_f32_e32 v22, v136, v22
	v_mul_f32_e32 v23, v136, v23
	v_mul_f32_e32 v24, v136, v24
	v_mul_f32_e32 v25, v136, v25
	v_mul_f32_e32 v18, v136, v18
	v_mul_f32_e32 v19, v136, v19
	v_mul_f32_e32 v20, v136, v20
	v_mul_f32_e32 v21, v136, v21
	v_pk_fma_f32 v[22:23], v[22:23], v[194:195], v[168:169]
	v_pk_fma_f32 v[24:25], v[24:25], v[196:197], v[170:171]
	v_pk_fma_f32 v[18:19], v[18:19], v[198:199], v[156:157]
	v_pk_fma_f32 v[20:21], v[20:21], v[200:201], v[158:159]
	v_cvt_pk_bf16_f32 v22, v22, v23
	v_cvt_pk_bf16_f32 v23, v24, v25
	v_cvt_pk_bf16_f32 v24, v18, v19
	v_cvt_pk_bf16_f32 v25, v20, v21
	global_store_dwordx4 v[154:155], v[22:25], off offset:256 sc1
	v_lshl_add_u64 v[154:155], v[154:155], 0, vcc
	v_mul_f32_e32 v14, v137, v14
	v_mul_f32_e32 v15, v137, v15
	v_mul_f32_e32 v16, v137, v16
	v_mul_f32_e32 v17, v137, v17
	v_mul_f32_e32 v10, v137, v10
	v_mul_f32_e32 v11, v137, v11
	v_mul_f32_e32 v12, v137, v12
	v_mul_f32_e32 v13, v137, v13
	v_pk_fma_f32 v[14:15], v[14:15], v[186:187], v[236:237]
	v_pk_fma_f32 v[16:17], v[16:17], v[188:189], v[238:239]
	v_pk_fma_f32 v[10:11], v[10:11], v[190:191], v[240:241]
	v_pk_fma_f32 v[12:13], v[12:13], v[192:193], v[242:243]
	v_cvt_pk_bf16_f32 v14, v14, v15
	v_cvt_pk_bf16_f32 v15, v16, v17
	v_cvt_pk_bf16_f32 v16, v10, v11
	v_cvt_pk_bf16_f32 v17, v12, v13
	global_store_dwordx4 v[154:155], v[14:17], off sc1
	v_mul_f32_e32 v6, v137, v6
	v_mul_f32_e32 v7, v137, v7
	v_mul_f32_e32 v8, v137, v8
	v_mul_f32_e32 v9, v137, v9
	v_mul_f32_e32 v2, v137, v2
	v_mul_f32_e32 v3, v137, v3
	v_mul_f32_e32 v4, v137, v4
	v_mul_f32_e32 v5, v137, v5
	v_pk_fma_f32 v[6:7], v[6:7], v[194:195], v[168:169]
	v_pk_fma_f32 v[8:9], v[8:9], v[196:197], v[170:171]
	v_pk_fma_f32 v[2:3], v[2:3], v[198:199], v[156:157]
	v_pk_fma_f32 v[4:5], v[4:5], v[200:201], v[158:159]
	v_cvt_pk_bf16_f32 v6, v6, v7
	v_cvt_pk_bf16_f32 v7, v8, v9
	v_cvt_pk_bf16_f32 v8, v2, v3
	v_cvt_pk_bf16_f32 v9, v4, v5
	global_store_dwordx4 v[154:155], v[6:9], off offset:256 sc1
	v_lshl_add_u64 v[154:155], v[154:155], 0, vcc
	s_branch .LBB0_348
.Lrf_last:
	global_load_dwordx4 v[186:189], v[222:223], off
	global_load_dwordx4 v[190:193], v[222:223], off offset:256
	v_lshl_add_u64 v[222:223], v[222:223], 0, vcc
	global_load_dwordx4 v[194:197], v[222:223], off
	global_load_dwordx4 v[198:201], v[222:223], off offset:256
	v_lshl_add_u64 v[222:223], v[222:223], 0, vcc
	global_load_dwordx4 v[202:205], v[222:223], off
	global_load_dwordx4 v[206:209], v[222:223], off offset:256
	v_lshl_add_u64 v[222:223], v[222:223], 0, vcc
	global_load_dwordx4 v[210:213], v[222:223], off
	global_load_dwordx4 v[214:217], v[222:223], off offset:256
	v_lshl_add_u64 v[222:223], v[222:223], 0, vcc
	v_lshl_add_u64 v[222:223], v[222:223], 0, s[28:29]
	global_load_dwordx4 v[218:221], v[222:223], off
	global_load_dwordx4 v[164:167], v[222:223], off offset:256
	v_lshl_add_u64 v[222:223], v[222:223], 0, vcc
	s_waitcnt vmcnt(9)
	v_pk_mul_f32 v[236:237], v[146:147], v[236:237]
	v_pk_mul_f32 v[238:239], v[146:147], v[238:239]
	v_pk_mul_f32 v[240:241], v[146:147], v[240:241]
	v_pk_mul_f32 v[242:243], v[146:147], v[242:243]
	v_pk_mul_f32 v[168:169], v[146:147], v[168:169]
	v_pk_mul_f32 v[170:171], v[146:147], v[170:171]
	v_pk_mul_f32 v[156:157], v[146:147], v[156:157]
	v_pk_mul_f32 v[158:159], v[146:147], v[158:159]
	v_lshlrev_b32_e32 v152, 16, v186
	v_and_b32_e32 v153, 0xffff0000, v186
	v_lshlrev_b32_e32 v160, 16, v187
	v_and_b32_e32 v161, 0xffff0000, v187
	v_lshlrev_b32_e32 v172, 16, v188
	v_and_b32_e32 v173, 0xffff0000, v188
	v_lshlrev_b32_e32 v162, 16, v189
	v_and_b32_e32 v163, 0xffff0000, v189
	global_load_dwordx4 v[186:189], v[222:223], off
	v_pk_mul_f32 v[126:127], v[126:127], v[236:237]
	v_pk_mul_f32 v[128:129], v[128:129], v[238:239]
	v_pk_mul_f32 v[122:123], v[122:123], v[240:241]
	v_pk_mul_f32 v[124:125], v[124:125], v[242:243]
	v_pk_add_f32 v[126:127], v[126:127], v[152:153]
	v_pk_add_f32 v[128:129], v[128:129], v[160:161]
	v_pk_add_f32 v[122:123], v[122:123], v[172:173]
	v_pk_add_f32 v[124:125], v[124:125], v[162:163]
	v_pk_mul_f32 v[152:153], v[126:127], v[126:127]
	v_pk_fma_f32 v[152:153], v[128:129], v[128:129], v[152:153]
	v_pk_fma_f32 v[152:153], v[122:123], v[122:123], v[152:153]
	v_pk_fma_f32 v[152:153], v[124:125], v[124:125], v[152:153]
	v_add_f32_e32 v130, v152, v153
	s_waitcnt vmcnt(9)
	v_lshlrev_b32_e32 v152, 16, v190
	v_and_b32_e32 v153, 0xffff0000, v190
	v_lshlrev_b32_e32 v160, 16, v191
	v_and_b32_e32 v161, 0xffff0000, v191
	v_lshlrev_b32_e32 v172, 16, v192
	v_and_b32_e32 v173, 0xffff0000, v192
	v_lshlrev_b32_e32 v162, 16, v193
	v_and_b32_e32 v163, 0xffff0000, v193
	global_load_dwordx4 v[190:193], v[222:223], off offset:256
	v_lshl_add_u64 v[222:223], v[222:223], 0, vcc
	v_pk_mul_f32 v[118:119], v[118:119], v[168:169]
	v_pk_mul_f32 v[120:121], v[120:121], v[170:171]
	v_pk_mul_f32 v[114:115], v[114:115], v[156:157]
	v_pk_mul_f32 v[116:117], v[116:117], v[158:159]
	v_pk_add_f32 v[118:119], v[118:119], v[152:153]
	v_pk_add_f32 v[120:121], v[120:121], v[160:161]
	v_pk_add_f32 v[114:115], v[114:115], v[172:173]
	v_pk_add_f32 v[116:117], v[116:117], v[162:163]
	v_pk_mul_f32 v[152:153], v[118:119], v[118:119]
	v_pk_fma_f32 v[152:153], v[120:121], v[120:121], v[152:153]
	v_pk_fma_f32 v[152:153], v[114:115], v[114:115], v[152:153]
	v_pk_fma_f32 v[152:153], v[116:117], v[116:117], v[152:153]
	v_add_f32_e32 v152, v152, v153
	v_add_f32_e32 v130, v130, v152
	s_waitcnt vmcnt(9)
	v_lshlrev_b32_e32 v152, 16, v194
	v_and_b32_e32 v153, 0xffff0000, v194
	v_lshlrev_b32_e32 v160, 16, v195
	v_and_b32_e32 v161, 0xffff0000, v195
	v_lshlrev_b32_e32 v172, 16, v196
	v_and_b32_e32 v173, 0xffff0000, v196
	v_lshlrev_b32_e32 v162, 16, v197
	v_and_b32_e32 v163, 0xffff0000, v197
	global_load_dwordx4 v[194:197], v[222:223], off
	v_pk_mul_f32 v[110:111], v[110:111], v[236:237]
	v_pk_mul_f32 v[112:113], v[112:113], v[238:239]
	v_pk_mul_f32 v[106:107], v[106:107], v[240:241]
	v_pk_mul_f32 v[108:109], v[108:109], v[242:243]
	v_pk_add_f32 v[110:111], v[110:111], v[152:153]
	v_pk_add_f32 v[112:113], v[112:113], v[160:161]
	v_pk_add_f32 v[106:107], v[106:107], v[172:173]
	v_pk_add_f32 v[108:109], v[108:109], v[162:163]
	v_pk_mul_f32 v[152:153], v[110:111], v[110:111]
	v_pk_fma_f32 v[152:153], v[112:113], v[112:113], v[152:153]
	v_pk_fma_f32 v[152:153], v[106:107], v[106:107], v[152:153]
	v_pk_fma_f32 v[152:153], v[108:109], v[108:109], v[152:153]
	v_add_f32_e32 v131, v152, v153
	s_waitcnt vmcnt(9)
	v_lshlrev_b32_e32 v152, 16, v198
	v_and_b32_e32 v153, 0xffff0000, v198
	v_lshlrev_b32_e32 v160, 16, v199
	v_and_b32_e32 v161, 0xffff0000, v199
	v_lshlrev_b32_e32 v172, 16, v200
	v_and_b32_e32 v173, 0xffff0000, v200
	v_lshlrev_b32_e32 v162, 16, v201
	v_and_b32_e32 v163, 0xffff0000, v201
	global_load_dwordx4 v[198:201], v[222:223], off offset:256
	v_lshl_add_u64 v[222:223], v[222:223], 0, vcc
	v_pk_mul_f32 v[102:103], v[102:103], v[168:169]
	v_pk_mul_f32 v[104:105], v[104:105], v[170:171]
	v_pk_mul_f32 v[98:99], v[98:99], v[156:157]
	v_pk_mul_f32 v[100:101], v[100:101], v[158:159]
	v_pk_add_f32 v[102:103], v[102:103], v[152:153]
	v_pk_add_f32 v[104:105], v[104:105], v[160:161]
	v_pk_add_f32 v[98:99], v[98:99], v[172:173]
	v_pk_add_f32 v[100:101], v[100:101], v[162:163]
	v_pk_mul_f32 v[152:153], v[102:103], v[102:103]
	v_pk_fma_f32 v[152:153], v[104:105], v[104:105], v[152:153]
	v_pk_fma_f32 v[152:153], v[98:99], v[98:99], v[152:153]
	v_pk_fma_f32 v[152:153], v[100:101], v[100:101], v[152:153]
	v_add_f32_e32 v152, v152, v153
	v_add_f32_e32 v131, v131, v152
	s_waitcnt vmcnt(9)
	v_lshlrev_b32_e32 v152, 16, v202
	v_and_b32_e32 v153, 0xffff0000, v202
	v_lshlrev_b32_e32 v160, 16, v203
	v_and_b32_e32 v161, 0xffff0000, v203
	v_lshlrev_b32_e32 v172, 16, v204
	v_and_b32_e32 v173, 0xffff0000, v204
	v_lshlrev_b32_e32 v162, 16, v205
	v_and_b32_e32 v163, 0xffff0000, v205
	global_load_dwordx4 v[202:205], v[222:223], off
	v_pk_mul_f32 v[94:95], v[94:95], v[236:237]
	v_pk_mul_f32 v[96:97], v[96:97], v[238:239]
	v_pk_mul_f32 v[90:91], v[90:91], v[240:241]
	v_pk_mul_f32 v[92:93], v[92:93], v[242:243]
	v_pk_add_f32 v[94:95], v[94:95], v[152:153]
	v_pk_add_f32 v[96:97], v[96:97], v[160:161]
	v_pk_add_f32 v[90:91], v[90:91], v[172:173]
	v_pk_add_f32 v[92:93], v[92:93], v[162:163]
	v_pk_mul_f32 v[152:153], v[94:95], v[94:95]
	v_pk_fma_f32 v[152:153], v[96:97], v[96:97], v[152:153]
	v_pk_fma_f32 v[152:153], v[90:91], v[90:91], v[152:153]
	v_pk_fma_f32 v[152:153], v[92:93], v[92:93], v[152:153]
	v_add_f32_e32 v132, v152, v153
	s_waitcnt vmcnt(9)
	v_lshlrev_b32_e32 v152, 16, v206
	v_and_b32_e32 v153, 0xffff0000, v206
	v_lshlrev_b32_e32 v160, 16, v207
	v_and_b32_e32 v161, 0xffff0000, v207
	v_lshlrev_b32_e32 v172, 16, v208
	v_and_b32_e32 v173, 0xffff0000, v208
	v_lshlrev_b32_e32 v162, 16, v209
	v_and_b32_e32 v163, 0xffff0000, v209
	global_load_dwordx4 v[206:209], v[222:223], off offset:256
	v_lshl_add_u64 v[222:223], v[222:223], 0, vcc
	v_pk_mul_f32 v[86:87], v[86:87], v[168:169]
	v_pk_mul_f32 v[88:89], v[88:89], v[170:171]
	v_pk_mul_f32 v[82:83], v[82:83], v[156:157]
	v_pk_mul_f32 v[84:85], v[84:85], v[158:159]
	v_pk_add_f32 v[86:87], v[86:87], v[152:153]
	v_pk_add_f32 v[88:89], v[88:89], v[160:161]
	v_pk_add_f32 v[82:83], v[82:83], v[172:173]
	v_pk_add_f32 v[84:85], v[84:85], v[162:163]
	v_pk_mul_f32 v[152:153], v[86:87], v[86:87]
	v_pk_fma_f32 v[152:153], v[88:89], v[88:89], v[152:153]
	v_pk_fma_f32 v[152:153], v[82:83], v[82:83], v[152:153]
	v_pk_fma_f32 v[152:153], v[84:85], v[84:85], v[152:153]
	v_add_f32_e32 v152, v152, v153
	v_add_f32_e32 v132, v132, v152
	s_waitcnt vmcnt(9)
	v_lshlrev_b32_e32 v152, 16, v210
	v_and_b32_e32 v153, 0xffff0000, v210
	v_lshlrev_b32_e32 v160, 16, v211
	v_and_b32_e32 v161, 0xffff0000, v211
	v_lshlrev_b32_e32 v172, 16, v212
	v_and_b32_e32 v173, 0xffff0000, v212
	v_lshlrev_b32_e32 v162, 16, v213
	v_and_b32_e32 v163, 0xffff0000, v213
	v_pk_mul_f32 v[78:79], v[78:79], v[236:237]
	v_pk_mul_f32 v[80:81], v[80:81], v[238:239]
	v_pk_mul_f32 v[74:75], v[74:75], v[240:241]
	v_pk_mul_f32 v[76:77], v[76:77], v[242:243]
	v_pk_add_f32 v[78:79], v[78:79], v[152:153]
	v_pk_add_f32 v[80:81], v[80:81], v[160:161]
	v_pk_add_f32 v[74:75], v[74:75], v[172:173]
	v_pk_add_f32 v[76:77], v[76:77], v[162:163]
	v_pk_mul_f32 v[152:153], v[78:79], v[78:79]
	v_pk_fma_f32 v[152:153], v[80:81], v[80:81], v[152:153]
	v_pk_fma_f32 v[152:153], v[74:75], v[74:75], v[152:153]
	v_pk_fma_f32 v[152:153], v[76:77], v[76:77], v[152:153]
	v_add_f32_e32 v133, v152, v153
	s_waitcnt vmcnt(8)
	v_lshlrev_b32_e32 v152, 16, v214
	v_and_b32_e32 v153, 0xffff0000, v214
	v_lshlrev_b32_e32 v160, 16, v215
	v_and_b32_e32 v161, 0xffff0000, v215
	v_lshlrev_b32_e32 v172, 16, v216
	v_and_b32_e32 v173, 0xffff0000, v216
	v_lshlrev_b32_e32 v162, 16, v217
	v_and_b32_e32 v163, 0xffff0000, v217
	v_pk_mul_f32 v[70:71], v[70:71], v[168:169]
	v_pk_mul_f32 v[72:73], v[72:73], v[170:171]
	v_pk_mul_f32 v[66:67], v[66:67], v[156:157]
	v_pk_mul_f32 v[68:69], v[68:69], v[158:159]
	v_pk_add_f32 v[70:71], v[70:71], v[152:153]
	v_pk_add_f32 v[72:73], v[72:73], v[160:161]
	v_pk_add_f32 v[66:67], v[66:67], v[172:173]
	v_pk_add_f32 v[68:69], v[68:69], v[162:163]
	v_pk_mul_f32 v[152:153], v[70:71], v[70:71]
	v_pk_fma_f32 v[152:153], v[72:73], v[72:73], v[152:153]
	v_pk_fma_f32 v[152:153], v[66:67], v[66:67], v[152:153]
	v_pk_fma_f32 v[152:153], v[68:69], v[68:69], v[152:153]
	v_add_f32_e32 v152, v152, v153
	v_add_f32_e32 v133, v133, v152
	s_waitcnt vmcnt(7)
	v_lshlrev_b32_e32 v152, 16, v218
	v_and_b32_e32 v153, 0xffff0000, v218
	v_lshlrev_b32_e32 v160, 16, v219
	v_and_b32_e32 v161, 0xffff0000, v219
	v_lshlrev_b32_e32 v172, 16, v220
	v_and_b32_e32 v173, 0xffff0000, v220
	v_lshlrev_b32_e32 v162, 16, v221
	v_and_b32_e32 v163, 0xffff0000, v221
	v_pk_mul_f32 v[62:63], v[62:63], v[236:237]
	v_pk_mul_f32 v[64:65], v[64:65], v[238:239]
	v_pk_mul_f32 v[58:59], v[58:59], v[240:241]
	v_pk_mul_f32 v[60:61], v[60:61], v[242:243]
	v_pk_add_f32 v[62:63], v[62:63], v[152:153]
	v_pk_add_f32 v[64:65], v[64:65], v[160:161]
	v_pk_add_f32 v[58:59], v[58:59], v[172:173]
	v_pk_add_f32 v[60:61], v[60:61], v[162:163]
	v_pk_mul_f32 v[152:153], v[62:63], v[62:63]
	v_pk_fma_f32 v[152:153], v[64:65], v[64:65], v[152:153]
	v_pk_fma_f32 v[152:153], v[58:59], v[58:59], v[152:153]
	v_pk_fma_f32 v[152:153], v[60:61], v[60:61], v[152:153]
	v_add_f32_e32 v134, v152, v153
	s_waitcnt vmcnt(6)
	v_lshlrev_b32_e32 v152, 16, v164
	v_and_b32_e32 v153, 0xffff0000, v164
	v_lshlrev_b32_e32 v160, 16, v165
	v_and_b32_e32 v161, 0xffff0000, v165
	v_lshlrev_b32_e32 v172, 16, v166
	v_and_b32_e32 v173, 0xffff0000, v166
	v_lshlrev_b32_e32 v162, 16, v167
	v_and_b32_e32 v163, 0xffff0000, v167
	v_pk_mul_f32 v[54:55], v[54:55], v[168:169]
	v_pk_mul_f32 v[56:57], v[56:57], v[170:171]
	v_pk_mul_f32 v[50:51], v[50:51], v[156:157]
	v_pk_mul_f32 v[52:53], v[52:53], v[158:159]
	v_pk_add_f32 v[54:55], v[54:55], v[152:153]
	v_pk_add_f32 v[56:57], v[56:57], v[160:161]
	v_pk_add_f32 v[50:51], v[50:51], v[172:173]
	v_pk_add_f32 v[52:53], v[52:53], v[162:163]
	v_pk_mul_f32 v[152:153], v[54:55], v[54:55]
	v_pk_fma_f32 v[152:153], v[56:57], v[56:57], v[152:153]
	v_pk_fma_f32 v[152:153], v[50:51], v[50:51], v[152:153]
	v_pk_fma_f32 v[152:153], v[52:53], v[52:53], v[152:153]
	v_add_f32_e32 v152, v152, v153
	v_add_f32_e32 v134, v134, v152
	s_waitcnt vmcnt(5)
	v_lshlrev_b32_e32 v152, 16, v186
	v_and_b32_e32 v153, 0xffff0000, v186
	v_lshlrev_b32_e32 v160, 16, v187
	v_and_b32_e32 v161, 0xffff0000, v187
	v_lshlrev_b32_e32 v172, 16, v188
	v_and_b32_e32 v173, 0xffff0000, v188
	v_lshlrev_b32_e32 v162, 16, v189
	v_and_b32_e32 v163, 0xffff0000, v189
	v_pk_mul_f32 v[46:47], v[46:47], v[236:237]
	v_pk_mul_f32 v[48:49], v[48:49], v[238:239]
	v_pk_mul_f32 v[42:43], v[42:43], v[240:241]
	v_pk_mul_f32 v[44:45], v[44:45], v[242:243]
	v_pk_add_f32 v[46:47], v[46:47], v[152:153]
	v_pk_add_f32 v[48:49], v[48:49], v[160:161]
	v_pk_add_f32 v[42:43], v[42:43], v[172:173]
	v_pk_add_f32 v[44:45], v[44:45], v[162:163]
	v_pk_mul_f32 v[152:153], v[46:47], v[46:47]
	v_pk_fma_f32 v[152:153], v[48:49], v[48:49], v[152:153]
	v_pk_fma_f32 v[152:153], v[42:43], v[42:43], v[152:153]
	v_pk_fma_f32 v[152:153], v[44:45], v[44:45], v[152:153]
	v_add_f32_e32 v135, v152, v153
	s_waitcnt vmcnt(4)
	v_lshlrev_b32_e32 v152, 16, v190
	v_and_b32_e32 v153, 0xffff0000, v190
	v_lshlrev_b32_e32 v160, 16, v191
	v_and_b32_e32 v161, 0xffff0000, v191
	v_lshlrev_b32_e32 v172, 16, v192
	v_and_b32_e32 v173, 0xffff0000, v192
	v_lshlrev_b32_e32 v162, 16, v193
	v_and_b32_e32 v163, 0xffff0000, v193
	v_pk_mul_f32 v[38:39], v[38:39], v[168:169]
	v_pk_mul_f32 v[40:41], v[40:41], v[170:171]
	v_pk_mul_f32 v[34:35], v[34:35], v[156:157]
	v_pk_mul_f32 v[36:37], v[36:37], v[158:159]
	v_pk_add_f32 v[38:39], v[38:39], v[152:153]
	v_pk_add_f32 v[40:41], v[40:41], v[160:161]
	v_pk_add_f32 v[34:35], v[34:35], v[172:173]
	v_pk_add_f32 v[36:37], v[36:37], v[162:163]
	v_pk_mul_f32 v[152:153], v[38:39], v[38:39]
	v_pk_fma_f32 v[152:153], v[40:41], v[40:41], v[152:153]
	v_pk_fma_f32 v[152:153], v[34:35], v[34:35], v[152:153]
	v_pk_fma_f32 v[152:153], v[36:37], v[36:37], v[152:153]
	v_add_f32_e32 v152, v152, v153
	v_add_f32_e32 v135, v135, v152
	s_waitcnt vmcnt(3)
	v_lshlrev_b32_e32 v152, 16, v194
	v_and_b32_e32 v153, 0xffff0000, v194
	v_lshlrev_b32_e32 v160, 16, v195
	v_and_b32_e32 v161, 0xffff0000, v195
	v_lshlrev_b32_e32 v172, 16, v196
	v_and_b32_e32 v173, 0xffff0000, v196
	v_lshlrev_b32_e32 v162, 16, v197
	v_and_b32_e32 v163, 0xffff0000, v197
	v_pk_mul_f32 v[30:31], v[30:31], v[236:237]
	v_pk_mul_f32 v[32:33], v[32:33], v[238:239]
	v_pk_mul_f32 v[26:27], v[26:27], v[240:241]
	v_pk_mul_f32 v[28:29], v[28:29], v[242:243]
	v_pk_add_f32 v[30:31], v[30:31], v[152:153]
	v_pk_add_f32 v[32:33], v[32:33], v[160:161]
	v_pk_add_f32 v[26:27], v[26:27], v[172:173]
	v_pk_add_f32 v[28:29], v[28:29], v[162:163]
	v_pk_mul_f32 v[152:153], v[30:31], v[30:31]
	v_pk_fma_f32 v[152:153], v[32:33], v[32:33], v[152:153]
	v_pk_fma_f32 v[152:153], v[26:27], v[26:27], v[152:153]
	v_pk_fma_f32 v[152:153], v[28:29], v[28:29], v[152:153]
	v_add_f32_e32 v136, v152, v153
	s_waitcnt vmcnt(2)
	v_lshlrev_b32_e32 v152, 16, v198
	v_and_b32_e32 v153, 0xffff0000, v198
	v_lshlrev_b32_e32 v160, 16, v199
	v_and_b32_e32 v161, 0xffff0000, v199
	v_lshlrev_b32_e32 v172, 16, v200
	v_and_b32_e32 v173, 0xffff0000, v200
	v_lshlrev_b32_e32 v162, 16, v201
	v_and_b32_e32 v163, 0xffff0000, v201
	v_pk_mul_f32 v[22:23], v[22:23], v[168:169]
	v_pk_mul_f32 v[24:25], v[24:25], v[170:171]
	v_pk_mul_f32 v[18:19], v[18:19], v[156:157]
	v_pk_mul_f32 v[20:21], v[20:21], v[158:159]
	v_pk_add_f32 v[22:23], v[22:23], v[152:153]
	v_pk_add_f32 v[24:25], v[24:25], v[160:161]
	v_pk_add_f32 v[18:19], v[18:19], v[172:173]
	v_pk_add_f32 v[20:21], v[20:21], v[162:163]
	v_pk_mul_f32 v[152:153], v[22:23], v[22:23]
	v_pk_fma_f32 v[152:153], v[24:25], v[24:25], v[152:153]
	v_pk_fma_f32 v[152:153], v[18:19], v[18:19], v[152:153]
	v_pk_fma_f32 v[152:153], v[20:21], v[20:21], v[152:153]
	v_add_f32_e32 v152, v152, v153
	v_add_f32_e32 v136, v136, v152
	s_waitcnt vmcnt(1)
	v_lshlrev_b32_e32 v152, 16, v202
	v_and_b32_e32 v153, 0xffff0000, v202
	v_lshlrev_b32_e32 v160, 16, v203
	v_and_b32_e32 v161, 0xffff0000, v203
	v_lshlrev_b32_e32 v172, 16, v204
	v_and_b32_e32 v173, 0xffff0000, v204
	v_lshlrev_b32_e32 v162, 16, v205
	v_and_b32_e32 v163, 0xffff0000, v205
	v_pk_mul_f32 v[14:15], v[14:15], v[236:237]
	v_pk_mul_f32 v[16:17], v[16:17], v[238:239]
	v_pk_mul_f32 v[10:11], v[10:11], v[240:241]
	v_pk_mul_f32 v[12:13], v[12:13], v[242:243]
	v_pk_add_f32 v[14:15], v[14:15], v[152:153]
	v_pk_add_f32 v[16:17], v[16:17], v[160:161]
	v_pk_add_f32 v[10:11], v[10:11], v[172:173]
	v_pk_add_f32 v[12:13], v[12:13], v[162:163]
	v_pk_mul_f32 v[152:153], v[14:15], v[14:15]
	v_pk_fma_f32 v[152:153], v[16:17], v[16:17], v[152:153]
	v_pk_fma_f32 v[152:153], v[10:11], v[10:11], v[152:153]
	v_pk_fma_f32 v[152:153], v[12:13], v[12:13], v[152:153]
	v_add_f32_e32 v137, v152, v153
	s_waitcnt vmcnt(0)
	v_lshlrev_b32_e32 v152, 16, v206
	v_and_b32_e32 v153, 0xffff0000, v206
	v_lshlrev_b32_e32 v160, 16, v207
	v_and_b32_e32 v161, 0xffff0000, v207
	v_lshlrev_b32_e32 v172, 16, v208
	v_and_b32_e32 v173, 0xffff0000, v208
	v_lshlrev_b32_e32 v162, 16, v209
	v_and_b32_e32 v163, 0xffff0000, v209
	v_pk_mul_f32 v[6:7], v[6:7], v[168:169]
	v_pk_mul_f32 v[8:9], v[8:9], v[170:171]
	v_pk_mul_f32 v[2:3], v[2:3], v[156:157]
	v_pk_mul_f32 v[4:5], v[4:5], v[158:159]
	v_pk_add_f32 v[6:7], v[6:7], v[152:153]
	v_pk_add_f32 v[8:9], v[8:9], v[160:161]
	v_pk_add_f32 v[2:3], v[2:3], v[172:173]
	v_pk_add_f32 v[4:5], v[4:5], v[162:163]
	v_pk_mul_f32 v[152:153], v[6:7], v[6:7]
	v_pk_fma_f32 v[152:153], v[8:9], v[8:9], v[152:153]
	v_pk_fma_f32 v[152:153], v[2:3], v[2:3], v[152:153]
	v_pk_fma_f32 v[152:153], v[4:5], v[4:5], v[152:153]
	v_add_f32_e32 v152, v152, v153
	v_add_f32_e32 v137, v137, v152
	v_mov_b32_e32 v206, v145
	v_mov_b32_e32 v207, v185
	s_waitcnt lgkmcnt(0)
	v_lshrrev_b32_e32 v145, 4, v224
	v_and_b32_e32 v145, 15, v145
	v_lshlrev_b32_e32 v145, 2, v145
	v_lshl_add_u32 v145, v174, 6, v145
	v_add_u32_e32 v145, 0xc000, v145
	ds_write_b32 v145, v130
	ds_write_b32 v145, v131 offset:1024
	ds_write_b32 v145, v132 offset:2048
	ds_write_b32 v145, v133 offset:3072
	ds_write_b32 v145, v134 offset:8192
	ds_write_b32 v145, v135 offset:9216
	ds_write_b32 v145, v136 offset:10240
	ds_write_b32 v145, v137 offset:11264
	s_waitcnt lgkmcnt(0)
	s_barrier
	v_cmp_gt_u32_e32 vcc, 0x100, v224
	s_and_saveexec_b64 s[30:31], vcc
	s_cbranch_execz .Lrf_x1_b
	v_lshlrev_b32_e32 v145, 6, v224
	v_add_u32_e32 v145, 0xc000, v145
	ds_read_b128 v[186:189], v145
	ds_read_b128 v[190:193], v145 offset:16
	ds_read_b128 v[194:197], v145 offset:32
	ds_read_b128 v[198:201], v145 offset:48
	s_lshl_b32 s13, s43, 2
	s_add_i32 s13, s13, s58
	s_lshl_b32 s13, s13, 10
	s_add_u32 s28, s40, 0x80000
	s_addc_u32 s29, s41, 0
	s_add_u32 s28, s28, s13
	s_addc_u32 s29, s29, 0
	v_lshlrev_b32_e32 v202, 2, v224
	s_waitcnt lgkmcnt(0)
	v_add_f32_e32 v186, v186, v187
	v_add_f32_e32 v188, v188, v189
	v_add_f32_e32 v186, v186, v188
	v_add_f32_e32 v190, v190, v191
	v_add_f32_e32 v192, v192, v193
	v_add_f32_e32 v190, v190, v192
	v_add_f32_e32 v194, v194, v195
	v_add_f32_e32 v196, v196, v197
	v_add_f32_e32 v194, v194, v196
	v_add_f32_e32 v198, v198, v199
	v_add_f32_e32 v200, v200, v201
	v_add_f32_e32 v198, v198, v200
	v_add_f32_e32 v186, v186, v190
	v_add_f32_e32 v194, v194, v198
	v_add_f32_e32 v186, v186, v194
	global_store_dword v202, v186, s[28:29] sc1
.Lrf_x1_b:
	s_or_b64 exec, exec, s[30:31]
	s_waitcnt vmcnt(0)
	s_barrier
	v_cmp_eq_u32_e32 vcc, 0, v224
	s_and_saveexec_b64 s[30:31], vcc
	s_cbranch_execz .Lrf_x2_b
	s_lshl_b32 s13, s43, 2
	s_add_u32 s28, s40, 0x70100
	s_addc_u32 s29, s41, 0
	s_add_u32 s28, s28, s13
	s_addc_u32 s29, s29, 0
	v_mov_b32_e32 v202, 1
	global_atomic_add v1, v202, s[28:29]
	s_mov_b32 s13, 0

.Lrf_x3_b:
	s_or_b64 exec, exec, s[30:31]
	s_waitcnt lgkmcnt(0)
	s_barrier
	v_lshlrev_b32_e32 v145, 2, v174
	v_add_u32_e32 v145, 0xc000, v145
	ds_read_b32 v130, v145
	ds_read_b32 v131, v145 offset:64
	ds_read_b32 v132, v145 offset:128
	ds_read_b32 v133, v145 offset:192
	ds_read_b32 v134, v145 offset:512
	ds_read_b32 v135, v145 offset:576
	ds_read_b32 v136, v145 offset:640
	ds_read_b32 v137, v145 offset:704
	s_load_dwordx2 s[28:29], s[0:1], 0x90
	s_load_dwordx2 s[30:31], s[0:1], 0x98
	v_lshl_or_b32 v202, s58, 8, v183
	v_lshlrev_b32_e32 v202, 2, v202
	v_mov_b32_e32 v203, 0
	s_waitcnt lgkmcnt(0)
	v_lshl_add_u64 v[204:205], s[28:29], 0, v[202:203]
	global_load_dwordx4 v[186:189], v[204:205], off
	global_load_dwordx4 v[190:193], v[204:205], off offset:16
	global_load_dwordx4 v[194:197], v[204:205], off offset:512
	global_load_dwordx4 v[198:201], v[204:205], off offset:528
	v_lshl_add_u64 v[154:155], v[206:207], 2, s[30:31]
	s_mov_b64 vcc, 0x10000
	s_mov_b64 s[28:29], 0x40000
	s_waitcnt vmcnt(0) lgkmcnt(0)
	v_mul_f32_e32 v126, v130, v126
	v_mul_f32_e32 v127, v130, v127
	v_mul_f32_e32 v128, v130, v128
	v_mul_f32_e32 v129, v130, v129
	v_mul_f32_e32 v122, v130, v122
	v_mul_f32_e32 v123, v130, v123
	v_mul_f32_e32 v124, v130, v124
	v_mul_f32_e32 v125, v130, v125
	v_pk_mul_f32 v[126:127], v[126:127], v[186:187]
	v_pk_mul_f32 v[128:129], v[128:129], v[188:189]
	v_pk_mul_f32 v[122:123], v[122:123], v[190:191]
	v_pk_mul_f32 v[124:125], v[124:125], v[192:193]
	global_store_dwordx4 v[154:155], v[126:129], off nt
	global_store_dwordx4 v[154:155], v[122:125], off offset:16 nt
	v_mul_f32_e32 v118, v130, v118
	v_mul_f32_e32 v119, v130, v119
	v_mul_f32_e32 v120, v130, v120
	v_mul_f32_e32 v121, v130, v121
	v_mul_f32_e32 v114, v130, v114
	v_mul_f32_e32 v115, v130, v115
	v_mul_f32_e32 v116, v130, v116
	v_mul_f32_e32 v117, v130, v117
	v_pk_mul_f32 v[118:119], v[118:119], v[194:195]
	v_pk_mul_f32 v[120:121], v[120:121], v[196:197]
	v_pk_mul_f32 v[114:115], v[114:115], v[198:199]
	v_pk_mul_f32 v[116:117], v[116:117], v[200:201]
	global_store_dwordx4 v[154:155], v[118:121], off offset:512 nt
	global_store_dwordx4 v[154:155], v[114:117], off offset:528 nt
	v_lshl_add_u64 v[154:155], v[154:155], 0, vcc
	v_mul_f32_e32 v110, v131, v110
	v_mul_f32_e32 v111, v131, v111
	v_mul_f32_e32 v112, v131, v112
	v_mul_f32_e32 v113, v131, v113
	v_mul_f32_e32 v106, v131, v106
	v_mul_f32_e32 v107, v131, v107
	v_mul_f32_e32 v108, v131, v108
	v_mul_f32_e32 v109, v131, v109
	v_pk_mul_f32 v[110:111], v[110:111], v[186:187]
	v_pk_mul_f32 v[112:113], v[112:113], v[188:189]
	v_pk_mul_f32 v[106:107], v[106:107], v[190:191]
	v_pk_mul_f32 v[108:109], v[108:109], v[192:193]
	global_store_dwordx4 v[154:155], v[110:113], off nt
	global_store_dwordx4 v[154:155], v[106:109], off offset:16 nt
	v_mul_f32_e32 v102, v131, v102
	v_mul_f32_e32 v103, v131, v103
	v_mul_f32_e32 v104, v131, v104
	v_mul_f32_e32 v105, v131, v105
	v_mul_f32_e32 v98, v131, v98
	v_mul_f32_e32 v99, v131, v99
	v_mul_f32_e32 v100, v131, v100
	v_mul_f32_e32 v101, v131, v101
	v_pk_mul_f32 v[102:103], v[102:103], v[194:195]
	v_pk_mul_f32 v[104:105], v[104:105], v[196:197]
	v_pk_mul_f32 v[98:99], v[98:99], v[198:199]
	v_pk_mul_f32 v[100:101], v[100:101], v[200:201]
	global_store_dwordx4 v[154:155], v[102:105], off offset:512 nt
	global_store_dwordx4 v[154:155], v[98:101], off offset:528 nt
	v_lshl_add_u64 v[154:155], v[154:155], 0, vcc
	v_mul_f32_e32 v94, v132, v94
	v_mul_f32_e32 v95, v132, v95
	v_mul_f32_e32 v96, v132, v96
	v_mul_f32_e32 v97, v132, v97
	v_mul_f32_e32 v90, v132, v90
	v_mul_f32_e32 v91, v132, v91
	v_mul_f32_e32 v92, v132, v92
	v_mul_f32_e32 v93, v132, v93
	v_pk_mul_f32 v[94:95], v[94:95], v[186:187]
	v_pk_mul_f32 v[96:97], v[96:97], v[188:189]
	v_pk_mul_f32 v[90:91], v[90:91], v[190:191]
	v_pk_mul_f32 v[92:93], v[92:93], v[192:193]
	global_store_dwordx4 v[154:155], v[94:97], off nt
	global_store_dwordx4 v[154:155], v[90:93], off offset:16 nt
	v_mul_f32_e32 v86, v132, v86
	v_mul_f32_e32 v87, v132, v87
	v_mul_f32_e32 v88, v132, v88
	v_mul_f32_e32 v89, v132, v89
	v_mul_f32_e32 v82, v132, v82
	v_mul_f32_e32 v83, v132, v83
	v_mul_f32_e32 v84, v132, v84
	v_mul_f32_e32 v85, v132, v85
	v_pk_mul_f32 v[86:87], v[86:87], v[194:195]
	v_pk_mul_f32 v[88:89], v[88:89], v[196:197]
	v_pk_mul_f32 v[82:83], v[82:83], v[198:199]
	v_pk_mul_f32 v[84:85], v[84:85], v[200:201]
	global_store_dwordx4 v[154:155], v[86:89], off offset:512 nt
	global_store_dwordx4 v[154:155], v[82:85], off offset:528 nt
	v_lshl_add_u64 v[154:155], v[154:155], 0, vcc
	v_mul_f32_e32 v78, v133, v78
	v_mul_f32_e32 v79, v133, v79
	v_mul_f32_e32 v80, v133, v80
	v_mul_f32_e32 v81, v133, v81
	v_mul_f32_e32 v74, v133, v74
	v_mul_f32_e32 v75, v133, v75
	v_mul_f32_e32 v76, v133, v76
	v_mul_f32_e32 v77, v133, v77
	v_pk_mul_f32 v[78:79], v[78:79], v[186:187]
	v_pk_mul_f32 v[80:81], v[80:81], v[188:189]
	v_pk_mul_f32 v[74:75], v[74:75], v[190:191]
	v_pk_mul_f32 v[76:77], v[76:77], v[192:193]
	global_store_dwordx4 v[154:155], v[78:81], off nt
	global_store_dwordx4 v[154:155], v[74:77], off offset:16 nt
	v_mul_f32_e32 v70, v133, v70
	v_mul_f32_e32 v71, v133, v71
	v_mul_f32_e32 v72, v133, v72
	v_mul_f32_e32 v73, v133, v73
	v_mul_f32_e32 v66, v133, v66
	v_mul_f32_e32 v67, v133, v67
	v_mul_f32_e32 v68, v133, v68
	v_mul_f32_e32 v69, v133, v69
	v_pk_mul_f32 v[70:71], v[70:71], v[194:195]
	v_pk_mul_f32 v[72:73], v[72:73], v[196:197]
	v_pk_mul_f32 v[66:67], v[66:67], v[198:199]
	v_pk_mul_f32 v[68:69], v[68:69], v[200:201]
	global_store_dwordx4 v[154:155], v[70:73], off offset:512 nt
	global_store_dwordx4 v[154:155], v[66:69], off offset:528 nt
	v_lshl_add_u64 v[154:155], v[154:155], 0, vcc
	v_lshl_add_u64 v[154:155], v[154:155], 0, s[28:29]
	v_mul_f32_e32 v62, v134, v62
	v_mul_f32_e32 v63, v134, v63
	v_mul_f32_e32 v64, v134, v64
	v_mul_f32_e32 v65, v134, v65
	v_mul_f32_e32 v58, v134, v58
	v_mul_f32_e32 v59, v134, v59
	v_mul_f32_e32 v60, v134, v60
	v_mul_f32_e32 v61, v134, v61
	v_pk_mul_f32 v[62:63], v[62:63], v[186:187]
	v_pk_mul_f32 v[64:65], v[64:65], v[188:189]
	v_pk_mul_f32 v[58:59], v[58:59], v[190:191]
	v_pk_mul_f32 v[60:61], v[60:61], v[192:193]
	global_store_dwordx4 v[154:155], v[62:65], off nt
	global_store_dwordx4 v[154:155], v[58:61], off offset:16 nt
	v_mul_f32_e32 v54, v134, v54
	v_mul_f32_e32 v55, v134, v55
	v_mul_f32_e32 v56, v134, v56
	v_mul_f32_e32 v57, v134, v57
	v_mul_f32_e32 v50, v134, v50
	v_mul_f32_e32 v51, v134, v51
	v_mul_f32_e32 v52, v134, v52
	v_mul_f32_e32 v53, v134, v53
	v_pk_mul_f32 v[54:55], v[54:55], v[194:195]
	v_pk_mul_f32 v[56:57], v[56:57], v[196:197]
	v_pk_mul_f32 v[50:51], v[50:51], v[198:199]
	v_pk_mul_f32 v[52:53], v[52:53], v[200:201]
	global_store_dwordx4 v[154:155], v[54:57], off offset:512 nt
	global_store_dwordx4 v[154:155], v[50:53], off offset:528 nt
	v_lshl_add_u64 v[154:155], v[154:155], 0, vcc
	v_mul_f32_e32 v46, v135, v46
	v_mul_f32_e32 v47, v135, v47
	v_mul_f32_e32 v48, v135, v48
	v_mul_f32_e32 v49, v135, v49
	v_mul_f32_e32 v42, v135, v42
	v_mul_f32_e32 v43, v135, v43
	v_mul_f32_e32 v44, v135, v44
	v_mul_f32_e32 v45, v135, v45
	v_pk_mul_f32 v[46:47], v[46:47], v[186:187]
	v_pk_mul_f32 v[48:49], v[48:49], v[188:189]
	v_pk_mul_f32 v[42:43], v[42:43], v[190:191]
	v_pk_mul_f32 v[44:45], v[44:45], v[192:193]
	global_store_dwordx4 v[154:155], v[46:49], off nt
	global_store_dwordx4 v[154:155], v[42:45], off offset:16 nt
	v_mul_f32_e32 v38, v135, v38
	v_mul_f32_e32 v39, v135, v39
	v_mul_f32_e32 v40, v135, v40
	v_mul_f32_e32 v41, v135, v41
	v_mul_f32_e32 v34, v135, v34
	v_mul_f32_e32 v35, v135, v35
	v_mul_f32_e32 v36, v135, v36
	v_mul_f32_e32 v37, v135, v37
	v_pk_mul_f32 v[38:39], v[38:39], v[194:195]
	v_pk_mul_f32 v[40:41], v[40:41], v[196:197]
	v_pk_mul_f32 v[34:35], v[34:35], v[198:199]
	v_pk_mul_f32 v[36:37], v[36:37], v[200:201]
	global_store_dwordx4 v[154:155], v[38:41], off offset:512 nt
	global_store_dwordx4 v[154:155], v[34:37], off offset:528 nt
	v_lshl_add_u64 v[154:155], v[154:155], 0, vcc
	v_mul_f32_e32 v30, v136, v30
	v_mul_f32_e32 v31, v136, v31
	v_mul_f32_e32 v32, v136, v32
	v_mul_f32_e32 v33, v136, v33
	v_mul_f32_e32 v26, v136, v26
	v_mul_f32_e32 v27, v136, v27
	v_mul_f32_e32 v28, v136, v28
	v_mul_f32_e32 v29, v136, v29
	v_pk_mul_f32 v[30:31], v[30:31], v[186:187]
	v_pk_mul_f32 v[32:33], v[32:33], v[188:189]
	v_pk_mul_f32 v[26:27], v[26:27], v[190:191]
	v_pk_mul_f32 v[28:29], v[28:29], v[192:193]
	global_store_dwordx4 v[154:155], v[30:33], off nt
	global_store_dwordx4 v[154:155], v[26:29], off offset:16 nt
	v_mul_f32_e32 v22, v136, v22
	v_mul_f32_e32 v23, v136, v23
	v_mul_f32_e32 v24, v136, v24
	v_mul_f32_e32 v25, v136, v25
	v_mul_f32_e32 v18, v136, v18
	v_mul_f32_e32 v19, v136, v19
	v_mul_f32_e32 v20, v136, v20
	v_mul_f32_e32 v21, v136, v21
	v_pk_mul_f32 v[22:23], v[22:23], v[194:195]
	v_pk_mul_f32 v[24:25], v[24:25], v[196:197]
	v_pk_mul_f32 v[18:19], v[18:19], v[198:199]
	v_pk_mul_f32 v[20:21], v[20:21], v[200:201]
	global_store_dwordx4 v[154:155], v[22:25], off offset:512 nt
	global_store_dwordx4 v[154:155], v[18:21], off offset:528 nt
	v_lshl_add_u64 v[154:155], v[154:155], 0, vcc
	v_mul_f32_e32 v14, v137, v14
	v_mul_f32_e32 v15, v137, v15
	v_mul_f32_e32 v16, v137, v16
	v_mul_f32_e32 v17, v137, v17
	v_mul_f32_e32 v10, v137, v10
	v_mul_f32_e32 v11, v137, v11
	v_mul_f32_e32 v12, v137, v12
	v_mul_f32_e32 v13, v137, v13
	v_pk_mul_f32 v[14:15], v[14:15], v[186:187]
	v_pk_mul_f32 v[16:17], v[16:17], v[188:189]
	v_pk_mul_f32 v[10:11], v[10:11], v[190:191]
	v_pk_mul_f32 v[12:13], v[12:13], v[192:193]
	global_store_dwordx4 v[154:155], v[14:17], off nt
	global_store_dwordx4 v[154:155], v[10:13], off offset:16 nt
	v_mul_f32_e32 v6, v137, v6
	v_mul_f32_e32 v7, v137, v7
	v_mul_f32_e32 v8, v137, v8
	v_mul_f32_e32 v9, v137, v9
	v_mul_f32_e32 v2, v137, v2
	v_mul_f32_e32 v3, v137, v3
	v_mul_f32_e32 v4, v137, v4
	v_mul_f32_e32 v5, v137, v5
	v_pk_mul_f32 v[6:7], v[6:7], v[194:195]
	v_pk_mul_f32 v[8:9], v[8:9], v[196:197]
	v_pk_mul_f32 v[2:3], v[2:3], v[198:199]
	v_pk_mul_f32 v[4:5], v[4:5], v[200:201]
	global_store_dwordx4 v[154:155], v[6:9], off offset:512 nt
	global_store_dwordx4 v[154:155], v[2:5], off offset:528 nt
	v_lshl_add_u64 v[154:155], v[154:155], 0, vcc
	s_branch .LBB0_348
.Lres_slow:
	global_load_dwordx4 v[130:133], v[162:163], off offset:16
	global_load_dwordx4 v[134:137], v[162:163], off
	v_mov_b32_e32 v145, v144
	s_cmp_gt_i32 s43, 63
	s_cselect_b64 s[30:31], -1, 0
	s_lshl_b32 s13, s43, 8
	s_cmp_lg_u32 s42, 0
	s_mov_b64 s[40:41], -1
	s_cselect_b64 s[28:29], -1, 0
	s_cmp_eq_u32 s42, 0
	s_waitcnt vmcnt(0)
	v_pk_mul_f32 v[156:157], v[144:145], v[132:133]
	v_pk_mul_f32 v[158:159], v[144:145], v[136:137]
	v_pk_mul_f32 v[160:161], v[146:147], v[134:135]
	v_pk_mul_f32 v[152:153], v[146:147], v[130:131]
	global_load_dwordx4 v[130:133], v[162:163], off offset:528
	global_load_dwordx4 v[134:137], v[162:163], off offset:512
	v_add_u32_e32 v162, s13, v174
	v_ashrrev_i32_e32 v163, 31, v162
	v_lshlrev_b64 v[162:163], 10, v[162:163]
	v_lshl_add_u64 v[162:163], v[162:163], 0, v[154:155]
	v_pk_mul_f32 v[168:169], v[128:129], v[158:159]
	v_pk_mul_f32 v[170:171], v[126:127], v[160:161]
	v_pk_mul_f32 v[164:165], v[124:125], v[156:157]
	v_pk_mul_f32 v[166:167], v[122:123], v[152:153]
	s_cbranch_scc1 .LBB0_222
	s_ashr_i32 s40, s12, 2
	s_ashr_i32 s41, s40, 31
	s_lshl_b64 s[40:41], s[40:41], 21
	s_add_u32 s40, s10, s40
	s_addc_u32 s41, s11, s41
	v_lshl_add_u64 v[126:127], v[162:163], 1, s[40:41]
	v_add_co_u32_e32 v126, vcc, 0xfe000000, v126
	v_cvt_pk_bf16_f32 v122, v170, v171
	v_cvt_pk_bf16_f32 v123, v168, v169
	v_cvt_pk_bf16_f32 v124, v166, v167
	v_cvt_pk_bf16_f32 v125, v164, v165
	v_addc_co_u32_e32 v127, vcc, -1, v127, vcc
	s_mov_b64 s[40:41], 0
	global_store_dwordx4 v[126:127], v[122:125], off sc1

.LBB0_584:
	s_ashr_i32 s17, s20, 6
	s_add_i32 s17, s17, s92
	v_readlane_b32 s18, v249, 49
	s_mul_i32 s19, s18, s17
	s_add_i32 s18, s19, s18
	s_min_i32 s23, s19, 0x4000
	s_cmp_lt_i32 s18, s23
	s_cbranch_scc1 .LBB0_605
	s_min_i32 s22, s18, 0x4000
	s_and_b64 s[6:7], s[6:7], exec
	s_movk_i32 s6, 0xc00
	s_cselect_b32 s18, s6, 0x1800
	s_and_b64 s[6:7], s[28:29], exec
	s_cselect_b32 s6, 0x2d000, 0
	s_waitcnt lgkmcnt(0)
	s_add_u32 s6, s8, s6
	s_addc_u32 s7, s9, 0
	s_and_b64 s[4:5], s[4:5], exec
	s_cselect_b32 s4, 0, s18
	s_lshl_b32 s4, s4, 2
	s_add_u32 s18, s6, s4
	s_addc_u32 s19, s7, 0
	s_and_b64 s[4:5], s[28:29], exec
	s_cselect_b32 s4, 0x1000, 0
	s_cmp_eq_u32 s3, 17
	s_movk_i32 s5, 0x4400
	s_cselect_b32 s24, 0x4000, s5
	s_add_i32 s6, s24, 0xffffc000
	s_add_u32 s14, s14, s4
	s_addc_u32 s15, s15, 0
	s_add_i32 s25, s17, 0x4000
	v_lshlrev_b32_e32 v0, 2, v2
	s_cmp_lg_u64 s[10:11], 0
	v_and_b32_e32 v3, 0xfc, v0
	s_cselect_b64 s[4:5], -1, 0
	s_cmp_lg_u32 s16, 0
	v_lshlrev_b32_e32 v0, 1, v3
	s_cselect_b64 s[20:21], -1, 0
	s_cmp_lt_i32 s17, s6
	v_lshl_add_u64 v[4:5], s[8:9], 0, v[0:1]
	v_lshl_add_u64 v[58:59], s[12:13], 0, v[0:1]
	v_and_b32_e32 v0, 63, v2
	s_cselect_b64 s[6:7], -1, 0
	s_mov_b64 s[8:9], 0x9000000
	s_and_b32 s26, s16, 3
	v_lshlrev_b32_e32 v0, 3, v0
	v_lshl_add_u64 v[50:51], v[4:5], 0, s[8:9]
	v_lshlrev_b32_e32 v6, 2, v3
	v_mov_b32_e32 v7, v1
	s_mov_b64 s[8:9], 0x4c00000
	s_cmp_gt_u32 s16, 3
	v_lshl_add_u64 v[2:3], s[12:13], 0, v[0:1]
	s_mov_b64 s[12:13], 0x400
	v_lshl_add_u64 v[52:53], s[14:15], 0, v[6:7]
	v_lshl_add_u64 v[54:55], v[4:5], 0, s[8:9]
	v_lshl_add_u64 v[56:57], s[10:11], 0, v[6:7]
	s_cselect_b64 s[8:9], -1, 0
	s_cmp_lg_u32 s26, 0
	v_lshl_add_u64 v[60:61], s[18:19], 0, v[6:7]
	s_mov_b64 s[14:15], 0x1000
	v_lshl_add_u64 v[64:65], v[2:3], 0, s[12:13]
	v_mov_b32_e32 v2, v1
	v_mov_b32_e32 v3, v1
	v_mov_b32_e32 v4, v1
	v_mov_b32_e32 v5, v1
	v_mov_b32_e32 v6, v1
	v_mov_b32_e32 v8, v1
	v_mov_b32_e32 v9, v1
	v_mov_b32_e32 v10, v1
	v_mov_b32_e32 v11, v1
	v_mov_b32_e32 v12, v1
	v_mov_b32_e32 v13, v1
	v_mov_b32_e32 v14, v1
	v_mov_b32_e32 v15, v1
	s_cselect_b64 s[10:11], -1, 0
	v_lshl_add_u64 v[62:63], v[60:61], 0, s[14:15]
	s_lshl_b32 s14, s16, 21
	v_mov_b32_e32 v0, v1
	v_mov_b64_e32 v[16:17], v[14:15]
	s_and_b32 s27, s14, 0x1800000
	s_mov_b32 s28, -1
	s_xor_b64 s[12:13], s[20:21], -1
	v_mov_b64_e32 v[14:15], v[12:13]
	v_mov_b64_e32 v[12:13], v[10:11]
	v_mov_b64_e32 v[10:11], v[8:9]
	v_mov_b64_e32 v[8:9], v[6:7]
	v_mov_b64_e32 v[6:7], v[4:5]
	v_mov_b64_e32 v[4:5], v[2:3]
	v_mov_b64_e32 v[2:3], v[0:1]
	s_cmp_eq_u32 s3, 17
	s_cbranch_scc0 .Lnf_go
	s_cmpk_eq_i32 s46, 0x100
	s_cbranch_scc0 .Lnf_go
	s_mov_b32 s23, s22
	s_branch .Lnf_skip
.Lnf_go:
	s_and_b64 vcc, exec, s[4:5]
	s_cbranch_vccnz .Lnf_skip
	s_sub_i32 vcc_lo, s22, s23
	s_cmp_lg_u32 vcc_lo, 8
	s_cbranch_scc1 .Lnf_skip
	s_lshr_b32 vcc_lo, s23, 12
	s_add_i32 vcc_hi, s22, -1
	s_lshr_b32 vcc_hi, vcc_hi, 12
	s_cmp_lg_u32 vcc_lo, vcc_hi
	s_cbranch_scc1 .Lnf_skip
	s_mul_i32 vcc_lo, vcc_lo, 0x9000
	s_mov_b32 vcc_hi, 0
	v_and_b32_e32 v114, 63, v224
	v_mov_b32_e32 v115, 0
	v_mov_b32_e32 v117, 0
	v_lshlrev_b32_e32 v116, 4, v114
	v_lshlrev_b32_e32 v114, 3, v114
	v_lshl_add_u64 v[118:119], v[52:53], 0, v[116:117]
	v_lshl_add_u64 v[120:121], v[62:63], 0, v[116:117]
	v_lshl_add_u64 v[194:195], v[60:61], 0, v[116:117]
	v_lshl_add_u64 v[120:121], v[120:121], 0, vcc
	v_lshl_add_u64 v[194:195], v[194:195], 0, vcc
	global_load_dwordx4 v[66:69], v[118:119], off
	global_load_dwordx4 v[70:73], v[118:119], off offset:16
	global_load_dwordx4 v[74:77], v[118:119], off offset:2048
	global_load_dwordx4 v[78:81], v[118:119], off offset:2064
	global_load_dwordx4 v[82:85], v[120:121], off
	global_load_dwordx4 v[86:89], v[120:121], off offset:16
	global_load_dwordx4 v[90:93], v[120:121], off offset:2048
	global_load_dwordx4 v[94:97], v[120:121], off offset:2064
	global_load_dwordx4 v[98:101], v[194:195], off
	global_load_dwordx4 v[102:105], v[194:195], off offset:16
	global_load_dwordx4 v[106:109], v[194:195], off offset:2048
	global_load_dwordx4 v[110:113], v[194:195], off offset:2064
	s_mov_b32 vcc_lo, s23
	s_lshl_b64 vcc, vcc, 11
	v_lshl_add_u64 v[186:187], v[54:55], 0, v[114:115]
	v_lshl_add_u64 v[186:187], v[186:187], 0, vcc
	s_mov_b64 vcc, 0x1000
	v_lshl_add_u64 v[188:189], v[186:187], 0, vcc
	v_lshl_add_u64 v[190:191], v[188:189], 0, vcc
	v_lshl_add_u64 v[192:193], v[190:191], 0, vcc
	global_load_dwordx4 v[122:125], v[186:187], off
	global_load_dwordx4 v[126:129], v[186:187], off offset:1024
	global_load_dwordx4 v[130:133], v[186:187], off offset:2048
	global_load_dwordx4 v[134:137], v[186:187], off offset:3072
	global_load_dwordx4 v[138:141], v[188:189], off
	global_load_dwordx4 v[142:145], v[188:189], off offset:1024
	global_load_dwordx4 v[146:149], v[188:189], off offset:2048
	global_load_dwordx4 v[150:153], v[188:189], off offset:3072
	global_load_dwordx4 v[154:157], v[190:191], off
	global_load_dwordx4 v[158:161], v[190:191], off offset:1024
	global_load_dwordx4 v[162:165], v[190:191], off offset:2048
	global_load_dwordx4 v[166:169], v[190:191], off offset:3072
	global_load_dwordx4 v[170:173], v[192:193], off
	global_load_dwordx4 v[174:177], v[192:193], off offset:1024
	global_load_dwordx4 v[178:181], v[192:193], off offset:2048
	global_load_dwordx4 v[182:185], v[192:193], off offset:3072
	v_mov_b32_e32 v220, 0x3a800000
	v_mov_b32_e32 v221, 0x358637bd
	s_mov_b64 vcc, 0x4400000
	v_lshl_add_u64 v[186:187], v[186:187], 0, vcc
	v_lshl_add_u64 v[188:189], v[188:189], 0, vcc
	v_lshl_add_u64 v[190:191], v[190:191], 0, vcc
	v_lshl_add_u64 v[192:193], v[192:193], 0, vcc
	s_waitcnt vmcnt(16)
	v_pk_add_f32 v[82:83], v[82:83], 1.0 op_sel_hi:[1,0]
	v_pk_add_f32 v[84:85], v[84:85], 1.0 op_sel_hi:[1,0]
	v_pk_add_f32 v[86:87], v[86:87], 1.0 op_sel_hi:[1,0]
	v_pk_add_f32 v[88:89], v[88:89], 1.0 op_sel_hi:[1,0]
	v_pk_add_f32 v[90:91], v[90:91], 1.0 op_sel_hi:[1,0]
	v_pk_add_f32 v[92:93], v[92:93], 1.0 op_sel_hi:[1,0]
	v_pk_add_f32 v[94:95], v[94:95], 1.0 op_sel_hi:[1,0]
	v_pk_add_f32 v[96:97], v[96:97], 1.0 op_sel_hi:[1,0]
	v_pk_mul_f32 v[66:67], v[66:67], v[82:83]
	v_pk_mul_f32 v[68:69], v[68:69], v[84:85]
	v_pk_mul_f32 v[70:71], v[70:71], v[86:87]
	v_pk_mul_f32 v[72:73], v[72:73], v[88:89]
	v_pk_mul_f32 v[74:75], v[74:75], v[90:91]
	v_pk_mul_f32 v[76:77], v[76:77], v[92:93]
	v_pk_mul_f32 v[78:79], v[78:79], v[94:95]
	v_pk_mul_f32 v[80:81], v[80:81], v[96:97]
	s_waitcnt vmcnt(14)
	v_lshlrev_b32_e32 v212, 16, v122
	v_and_b32_e32 v213, 0xffff0000, v122
	v_mul_f32_e32 v82, v212, v212
	v_mul_f32_e32 v83, v213, v213
	v_lshlrev_b32_e32 v214, 16, v123
	v_and_b32_e32 v215, 0xffff0000, v123
	v_fmac_f32_e32 v82, v214, v214
	v_fmac_f32_e32 v83, v215, v215
	v_lshlrev_b32_e32 v216, 16, v124
	v_and_b32_e32 v217, 0xffff0000, v124
	v_fmac_f32_e32 v82, v216, v216
	v_fmac_f32_e32 v83, v217, v217
	v_lshlrev_b32_e32 v218, 16, v125
	v_and_b32_e32 v219, 0xffff0000, v125
	v_fmac_f32_e32 v82, v218, v218
	v_fmac_f32_e32 v83, v219, v219
	v_lshlrev_b32_e32 v212, 16, v126
	v_and_b32_e32 v213, 0xffff0000, v126
	v_fmac_f32_e32 v82, v212, v212
	v_fmac_f32_e32 v83, v213, v213
	v_lshlrev_b32_e32 v214, 16, v127
	v_and_b32_e32 v215, 0xffff0000, v127
	v_fmac_f32_e32 v82, v214, v214
	v_fmac_f32_e32 v83, v215, v215
	v_lshlrev_b32_e32 v216, 16, v128
	v_and_b32_e32 v217, 0xffff0000, v128
	v_fmac_f32_e32 v82, v216, v216
	v_fmac_f32_e32 v83, v217, v217
	v_lshlrev_b32_e32 v218, 16, v129
	v_and_b32_e32 v219, 0xffff0000, v129
	v_fmac_f32_e32 v82, v218, v218
	v_fmac_f32_e32 v83, v219, v219
	s_waitcnt vmcnt(12)
	v_lshlrev_b32_e32 v212, 16, v130
	v_and_b32_e32 v213, 0xffff0000, v130
	v_mul_f32_e32 v84, v212, v212
	v_mul_f32_e32 v85, v213, v213
	v_lshlrev_b32_e32 v214, 16, v131
	v_and_b32_e32 v215, 0xffff0000, v131
	v_fmac_f32_e32 v84, v214, v214
	v_fmac_f32_e32 v85, v215, v215
	v_lshlrev_b32_e32 v216, 16, v132
	v_and_b32_e32 v217, 0xffff0000, v132
	v_fmac_f32_e32 v84, v216, v216
	v_fmac_f32_e32 v85, v217, v217
	v_lshlrev_b32_e32 v218, 16, v133
	v_and_b32_e32 v219, 0xffff0000, v133
	v_fmac_f32_e32 v84, v218, v218
	v_fmac_f32_e32 v85, v219, v219
	v_lshlrev_b32_e32 v212, 16, v134
	v_and_b32_e32 v213, 0xffff0000, v134
	v_fmac_f32_e32 v84, v212, v212
	v_fmac_f32_e32 v85, v213, v213
	v_lshlrev_b32_e32 v214, 16, v135
	v_and_b32_e32 v215, 0xffff0000, v135
	v_fmac_f32_e32 v84, v214, v214
	v_fmac_f32_e32 v85, v215, v215
	v_lshlrev_b32_e32 v216, 16, v136
	v_and_b32_e32 v217, 0xffff0000, v136
	v_fmac_f32_e32 v84, v216, v216
	v_fmac_f32_e32 v85, v217, v217
	v_lshlrev_b32_e32 v218, 16, v137
	v_and_b32_e32 v219, 0xffff0000, v137
	v_fmac_f32_e32 v84, v218, v218
	v_fmac_f32_e32 v85, v219, v219
	s_waitcnt vmcnt(10)
	v_lshlrev_b32_e32 v212, 16, v138
	v_and_b32_e32 v213, 0xffff0000, v138
	v_mul_f32_e32 v86, v212, v212
	v_mul_f32_e32 v87, v213, v213
	v_lshlrev_b32_e32 v214, 16, v139
	v_and_b32_e32 v215, 0xffff0000, v139
	v_fmac_f32_e32 v86, v214, v214
	v_fmac_f32_e32 v87, v215, v215
	v_lshlrev_b32_e32 v216, 16, v140
	v_and_b32_e32 v217, 0xffff0000, v140
	v_fmac_f32_e32 v86, v216, v216
	v_fmac_f32_e32 v87, v217, v217
	v_lshlrev_b32_e32 v218, 16, v141
	v_and_b32_e32 v219, 0xffff0000, v141
	v_fmac_f32_e32 v86, v218, v218
	v_fmac_f32_e32 v87, v219, v219
	v_lshlrev_b32_e32 v212, 16, v142
	v_and_b32_e32 v213, 0xffff0000, v142
	v_fmac_f32_e32 v86, v212, v212
	v_fmac_f32_e32 v87, v213, v213
	v_lshlrev_b32_e32 v214, 16, v143
	v_and_b32_e32 v215, 0xffff0000, v143
	v_fmac_f32_e32 v86, v214, v214
	v_fmac_f32_e32 v87, v215, v215
	v_lshlrev_b32_e32 v216, 16, v144
	v_and_b32_e32 v217, 0xffff0000, v144
	v_fmac_f32_e32 v86, v216, v216
	v_fmac_f32_e32 v87, v217, v217
	v_lshlrev_b32_e32 v218, 16, v145
	v_and_b32_e32 v219, 0xffff0000, v145
	v_fmac_f32_e32 v86, v218, v218
	v_fmac_f32_e32 v87, v219, v219
	s_waitcnt vmcnt(8)
	v_lshlrev_b32_e32 v212, 16, v146
	v_and_b32_e32 v213, 0xffff0000, v146
	v_mul_f32_e32 v88, v212, v212
	v_mul_f32_e32 v89, v213, v213
	v_lshlrev_b32_e32 v214, 16, v147
	v_and_b32_e32 v215, 0xffff0000, v147
	v_fmac_f32_e32 v88, v214, v214
	v_fmac_f32_e32 v89, v215, v215
	v_lshlrev_b32_e32 v216, 16, v148
	v_and_b32_e32 v217, 0xffff0000, v148
	v_fmac_f32_e32 v88, v216, v216
	v_fmac_f32_e32 v89, v217, v217
	v_lshlrev_b32_e32 v218, 16, v149
	v_and_b32_e32 v219, 0xffff0000, v149
	v_fmac_f32_e32 v88, v218, v218
	v_fmac_f32_e32 v89, v219, v219
	v_lshlrev_b32_e32 v212, 16, v150
	v_and_b32_e32 v213, 0xffff0000, v150
	v_fmac_f32_e32 v88, v212, v212
	v_fmac_f32_e32 v89, v213, v213
	v_lshlrev_b32_e32 v214, 16, v151
	v_and_b32_e32 v215, 0xffff0000, v151
	v_fmac_f32_e32 v88, v214, v214
	v_fmac_f32_e32 v89, v215, v215
	v_lshlrev_b32_e32 v216, 16, v152
	v_and_b32_e32 v217, 0xffff0000, v152
	v_fmac_f32_e32 v88, v216, v216
	v_fmac_f32_e32 v89, v217, v217
	v_lshlrev_b32_e32 v218, 16, v153
	v_and_b32_e32 v219, 0xffff0000, v153
	v_fmac_f32_e32 v88, v218, v218
	v_fmac_f32_e32 v89, v219, v219
	s_waitcnt vmcnt(6)
	v_lshlrev_b32_e32 v212, 16, v154
	v_and_b32_e32 v213, 0xffff0000, v154
	v_mul_f32_e32 v90, v212, v212
	v_mul_f32_e32 v91, v213, v213
	v_lshlrev_b32_e32 v214, 16, v155
	v_and_b32_e32 v215, 0xffff0000, v155
	v_fmac_f32_e32 v90, v214, v214
	v_fmac_f32_e32 v91, v215, v215
	v_lshlrev_b32_e32 v216, 16, v156
	v_and_b32_e32 v217, 0xffff0000, v156
	v_fmac_f32_e32 v90, v216, v216
	v_fmac_f32_e32 v91, v217, v217
	v_lshlrev_b32_e32 v218, 16, v157
	v_and_b32_e32 v219, 0xffff0000, v157
	v_fmac_f32_e32 v90, v218, v218
	v_fmac_f32_e32 v91, v219, v219
	v_lshlrev_b32_e32 v212, 16, v158
	v_and_b32_e32 v213, 0xffff0000, v158
	v_fmac_f32_e32 v90, v212, v212
	v_fmac_f32_e32 v91, v213, v213
	v_lshlrev_b32_e32 v214, 16, v159
	v_and_b32_e32 v215, 0xffff0000, v159
	v_fmac_f32_e32 v90, v214, v214
	v_fmac_f32_e32 v91, v215, v215
	v_lshlrev_b32_e32 v216, 16, v160
	v_and_b32_e32 v217, 0xffff0000, v160
	v_fmac_f32_e32 v90, v216, v216
	v_fmac_f32_e32 v91, v217, v217
	v_lshlrev_b32_e32 v218, 16, v161
	v_and_b32_e32 v219, 0xffff0000, v161
	v_fmac_f32_e32 v90, v218, v218
	v_fmac_f32_e32 v91, v219, v219
	s_waitcnt vmcnt(4)
	v_lshlrev_b32_e32 v212, 16, v162
	v_and_b32_e32 v213, 0xffff0000, v162
	v_mul_f32_e32 v92, v212, v212
	v_mul_f32_e32 v93, v213, v213
	v_lshlrev_b32_e32 v214, 16, v163
	v_and_b32_e32 v215, 0xffff0000, v163
	v_fmac_f32_e32 v92, v214, v214
	v_fmac_f32_e32 v93, v215, v215
	v_lshlrev_b32_e32 v216, 16, v164
	v_and_b32_e32 v217, 0xffff0000, v164
	v_fmac_f32_e32 v92, v216, v216
	v_fmac_f32_e32 v93, v217, v217
	v_lshlrev_b32_e32 v218, 16, v165
	v_and_b32_e32 v219, 0xffff0000, v165
	v_fmac_f32_e32 v92, v218, v218
	v_fmac_f32_e32 v93, v219, v219
	v_lshlrev_b32_e32 v212, 16, v166
	v_and_b32_e32 v213, 0xffff0000, v166
	v_fmac_f32_e32 v92, v212, v212
	v_fmac_f32_e32 v93, v213, v213
	v_lshlrev_b32_e32 v214, 16, v167
	v_and_b32_e32 v215, 0xffff0000, v167
	v_fmac_f32_e32 v92, v214, v214
	v_fmac_f32_e32 v93, v215, v215
	v_lshlrev_b32_e32 v216, 16, v168
	v_and_b32_e32 v217, 0xffff0000, v168
	v_fmac_f32_e32 v92, v216, v216
	v_fmac_f32_e32 v93, v217, v217
	v_lshlrev_b32_e32 v218, 16, v169
	v_and_b32_e32 v219, 0xffff0000, v169
	v_fmac_f32_e32 v92, v218, v218
	v_fmac_f32_e32 v93, v219, v219
	s_waitcnt vmcnt(2)
	v_lshlrev_b32_e32 v212, 16, v170
	v_and_b32_e32 v213, 0xffff0000, v170
	v_mul_f32_e32 v94, v212, v212
	v_mul_f32_e32 v95, v213, v213
	v_lshlrev_b32_e32 v214, 16, v171
	v_and_b32_e32 v215, 0xffff0000, v171
	v_fmac_f32_e32 v94, v214, v214
	v_fmac_f32_e32 v95, v215, v215
	v_lshlrev_b32_e32 v216, 16, v172
	v_and_b32_e32 v217, 0xffff0000, v172
	v_fmac_f32_e32 v94, v216, v216
	v_fmac_f32_e32 v95, v217, v217
	v_lshlrev_b32_e32 v218, 16, v173
	v_and_b32_e32 v219, 0xffff0000, v173
	v_fmac_f32_e32 v94, v218, v218
	v_fmac_f32_e32 v95, v219, v219
	v_lshlrev_b32_e32 v212, 16, v174
	v_and_b32_e32 v213, 0xffff0000, v174
	v_fmac_f32_e32 v94, v212, v212
	v_fmac_f32_e32 v95, v213, v213
	v_lshlrev_b32_e32 v214, 16, v175
	v_and_b32_e32 v215, 0xffff0000, v175
	v_fmac_f32_e32 v94, v214, v214
	v_fmac_f32_e32 v95, v215, v215
	v_lshlrev_b32_e32 v216, 16, v176
	v_and_b32_e32 v217, 0xffff0000, v176
	v_fmac_f32_e32 v94, v216, v216
	v_fmac_f32_e32 v95, v217, v217
	v_lshlrev_b32_e32 v218, 16, v177
	v_and_b32_e32 v219, 0xffff0000, v177
	v_fmac_f32_e32 v94, v218, v218
	v_fmac_f32_e32 v95, v219, v219
	s_waitcnt vmcnt(0)
	v_lshlrev_b32_e32 v212, 16, v178
	v_and_b32_e32 v213, 0xffff0000, v178
	v_mul_f32_e32 v96, v212, v212
	v_mul_f32_e32 v97, v213, v213
	v_lshlrev_b32_e32 v214, 16, v179
	v_and_b32_e32 v215, 0xffff0000, v179
	v_fmac_f32_e32 v96, v214, v214
	v_fmac_f32_e32 v97, v215, v215
	v_lshlrev_b32_e32 v216, 16, v180
	v_and_b32_e32 v217, 0xffff0000, v180
	v_fmac_f32_e32 v96, v216, v216
	v_fmac_f32_e32 v97, v217, v217
	v_lshlrev_b32_e32 v218, 16, v181
	v_and_b32_e32 v219, 0xffff0000, v181
	v_fmac_f32_e32 v96, v218, v218
	v_fmac_f32_e32 v97, v219, v219
	v_lshlrev_b32_e32 v212, 16, v182
	v_and_b32_e32 v213, 0xffff0000, v182
	v_fmac_f32_e32 v96, v212, v212
	v_fmac_f32_e32 v97, v213, v213
	v_lshlrev_b32_e32 v214, 16, v183
	v_and_b32_e32 v215, 0xffff0000, v183
	v_fmac_f32_e32 v96, v214, v214
	v_fmac_f32_e32 v97, v215, v215
	v_lshlrev_b32_e32 v216, 16, v184
	v_and_b32_e32 v217, 0xffff0000, v184
	v_fmac_f32_e32 v96, v216, v216
	v_fmac_f32_e32 v97, v217, v217
	v_lshlrev_b32_e32 v218, 16, v185
	v_and_b32_e32 v219, 0xffff0000, v185
	v_fmac_f32_e32 v96, v218, v218
	v_fmac_f32_e32 v97, v219, v219
	v_add_f32_e32 v82, v82, v83
	v_add_f32_e32 v84, v84, v85
	v_add_f32_e32 v86, v86, v87
	v_add_f32_e32 v88, v88, v89
	v_add_f32_e32 v90, v90, v91
	v_add_f32_e32 v92, v92, v93
	v_add_f32_e32 v94, v94, v95
	v_add_f32_e32 v96, v96, v97
	v_add_f32_dpp v82, v82, v82 quad_perm:[1,0,3,2] row_mask:0xf bank_mask:0xf
	v_add_f32_dpp v84, v84, v84 quad_perm:[1,0,3,2] row_mask:0xf bank_mask:0xf
	v_add_f32_dpp v86, v86, v86 quad_perm:[1,0,3,2] row_mask:0xf bank_mask:0xf
	v_add_f32_dpp v88, v88, v88 quad_perm:[1,0,3,2] row_mask:0xf bank_mask:0xf
	v_add_f32_dpp v90, v90, v90 quad_perm:[1,0,3,2] row_mask:0xf bank_mask:0xf
	v_add_f32_dpp v92, v92, v92 quad_perm:[1,0,3,2] row_mask:0xf bank_mask:0xf
	v_add_f32_dpp v94, v94, v94 quad_perm:[1,0,3,2] row_mask:0xf bank_mask:0xf
	v_add_f32_dpp v96, v96, v96 quad_perm:[1,0,3,2] row_mask:0xf bank_mask:0xf
	v_add_f32_dpp v82, v82, v82 quad_perm:[2,3,0,1] row_mask:0xf bank_mask:0xf
	v_add_f32_dpp v84, v84, v84 quad_perm:[2,3,0,1] row_mask:0xf bank_mask:0xf
	v_add_f32_dpp v86, v86, v86 quad_perm:[2,3,0,1] row_mask:0xf bank_mask:0xf
	v_add_f32_dpp v88, v88, v88 quad_perm:[2,3,0,1] row_mask:0xf bank_mask:0xf
	v_add_f32_dpp v90, v90, v90 quad_perm:[2,3,0,1] row_mask:0xf bank_mask:0xf
	v_add_f32_dpp v92, v92, v92 quad_perm:[2,3,0,1] row_mask:0xf bank_mask:0xf
	v_add_f32_dpp v94, v94, v94 quad_perm:[2,3,0,1] row_mask:0xf bank_mask:0xf
	v_add_f32_dpp v96, v96, v96 quad_perm:[2,3,0,1] row_mask:0xf bank_mask:0xf
	v_add_f32_dpp v82, v82, v82 row_half_mirror row_mask:0xf bank_mask:0xf
	v_add_f32_dpp v84, v84, v84 row_half_mirror row_mask:0xf bank_mask:0xf
	v_add_f32_dpp v86, v86, v86 row_half_mirror row_mask:0xf bank_mask:0xf
	v_add_f32_dpp v88, v88, v88 row_half_mirror row_mask:0xf bank_mask:0xf
	v_add_f32_dpp v90, v90, v90 row_half_mirror row_mask:0xf bank_mask:0xf
	v_add_f32_dpp v92, v92, v92 row_half_mirror row_mask:0xf bank_mask:0xf
	v_add_f32_dpp v94, v94, v94 row_half_mirror row_mask:0xf bank_mask:0xf
	v_add_f32_dpp v96, v96, v96 row_half_mirror row_mask:0xf bank_mask:0xf
	v_add_f32_dpp v82, v82, v82 row_mirror row_mask:0xf bank_mask:0xf
	v_add_f32_dpp v84, v84, v84 row_mirror row_mask:0xf bank_mask:0xf
	v_add_f32_dpp v86, v86, v86 row_mirror row_mask:0xf bank_mask:0xf
	v_add_f32_dpp v88, v88, v88 row_mirror row_mask:0xf bank_mask:0xf
	v_add_f32_dpp v90, v90, v90 row_mirror row_mask:0xf bank_mask:0xf
	v_add_f32_dpp v92, v92, v92 row_mirror row_mask:0xf bank_mask:0xf
	v_add_f32_dpp v94, v94, v94 row_mirror row_mask:0xf bank_mask:0xf
	v_add_f32_dpp v96, v96, v96 row_mirror row_mask:0xf bank_mask:0xf
	v_add_f32_dpp v82, v82, v82 row_bcast:15 row_mask:0xa bank_mask:0xf
	v_add_f32_dpp v84, v84, v84 row_bcast:15 row_mask:0xa bank_mask:0xf
	v_add_f32_dpp v86, v86, v86 row_bcast:15 row_mask:0xa bank_mask:0xf
	v_add_f32_dpp v88, v88, v88 row_bcast:15 row_mask:0xa bank_mask:0xf
	v_add_f32_dpp v90, v90, v90 row_bcast:15 row_mask:0xa bank_mask:0xf
	v_add_f32_dpp v92, v92, v92 row_bcast:15 row_mask:0xa bank_mask:0xf
	v_add_f32_dpp v94, v94, v94 row_bcast:15 row_mask:0xa bank_mask:0xf
	v_add_f32_dpp v96, v96, v96 row_bcast:15 row_mask:0xa bank_mask:0xf
	v_add_f32_dpp v82, v82, v82 row_bcast:31 row_mask:0xc bank_mask:0xf
	v_add_f32_dpp v84, v84, v84 row_bcast:31 row_mask:0xc bank_mask:0xf
	v_add_f32_dpp v86, v86, v86 row_bcast:31 row_mask:0xc bank_mask:0xf
	v_add_f32_dpp v88, v88, v88 row_bcast:31 row_mask:0xc bank_mask:0xf
	v_add_f32_dpp v90, v90, v90 row_bcast:31 row_mask:0xc bank_mask:0xf
	v_add_f32_dpp v92, v92, v92 row_bcast:31 row_mask:0xc bank_mask:0xf
	v_add_f32_dpp v94, v94, v94 row_bcast:31 row_mask:0xc bank_mask:0xf
	v_add_f32_dpp v96, v96, v96 row_bcast:31 row_mask:0xc bank_mask:0xf
	v_readlane_b32 vcc_lo, v82, 63
	v_readlane_b32 vcc_hi, v84, 63
	s_nop 1
	v_fma_f32 v196, vcc_lo, v220, v221
	v_fma_f32 v198, vcc_hi, v220, v221
	s_nop 1
	v_readlane_b32 vcc_lo, v86, 63
	v_readlane_b32 vcc_hi, v88, 63
	s_nop 1
	v_fma_f32 v200, vcc_lo, v220, v221
	v_fma_f32 v202, vcc_hi, v220, v221
	s_nop 1
	v_readlane_b32 vcc_lo, v90, 63
	v_readlane_b32 vcc_hi, v92, 63
	s_nop 1
	v_fma_f32 v204, vcc_lo, v220, v221
	v_fma_f32 v206, vcc_hi, v220, v221
	s_nop 1
	v_readlane_b32 vcc_lo, v94, 63
	v_readlane_b32 vcc_hi, v96, 63
	s_nop 1
	v_fma_f32 v208, vcc_lo, v220, v221
	v_fma_f32 v210, vcc_hi, v220, v221
	s_nop 1
	v_rsq_f32_e32 v196, v196
	v_rsq_f32_e32 v198, v198
	v_rsq_f32_e32 v200, v200
	v_rsq_f32_e32 v202, v202
	v_rsq_f32_e32 v204, v204
	v_rsq_f32_e32 v206, v206
	v_rsq_f32_e32 v208, v208
	v_rsq_f32_e32 v210, v210
	s_nop 1
	v_lshlrev_b32_e32 v212, 16, v122
	v_and_b32_e32 v213, 0xffff0000, v122
	v_pk_mul_f32 v[212:213], v[212:213], v[196:197] op_sel_hi:[1,0]
	v_pk_fma_f32 v[212:213], v[212:213], v[66:67], v[98:99]
	v_cvt_pk_bf16_f32 v122, v212, v213
	v_lshlrev_b32_e32 v214, 16, v123
	v_and_b32_e32 v215, 0xffff0000, v123
	v_pk_mul_f32 v[214:215], v[214:215], v[196:197] op_sel_hi:[1,0]
	v_pk_fma_f32 v[214:215], v[214:215], v[68:69], v[100:101]
	v_cvt_pk_bf16_f32 v123, v214, v215
	v_lshlrev_b32_e32 v216, 16, v124
	v_and_b32_e32 v217, 0xffff0000, v124
	v_pk_mul_f32 v[216:217], v[216:217], v[196:197] op_sel_hi:[1,0]
	v_pk_fma_f32 v[216:217], v[216:217], v[70:71], v[102:103]
	v_cvt_pk_bf16_f32 v124, v216, v217
	v_lshlrev_b32_e32 v218, 16, v125
	v_and_b32_e32 v219, 0xffff0000, v125
	v_pk_mul_f32 v[218:219], v[218:219], v[196:197] op_sel_hi:[1,0]
	v_pk_fma_f32 v[218:219], v[218:219], v[72:73], v[104:105]
	v_cvt_pk_bf16_f32 v125, v218, v219
	v_lshlrev_b32_e32 v212, 16, v126
	v_and_b32_e32 v213, 0xffff0000, v126
	v_pk_mul_f32 v[212:213], v[212:213], v[196:197] op_sel_hi:[1,0]
	v_pk_fma_f32 v[212:213], v[212:213], v[74:75], v[106:107]
	v_cvt_pk_bf16_f32 v126, v212, v213
	v_lshlrev_b32_e32 v214, 16, v127
	v_and_b32_e32 v215, 0xffff0000, v127
	v_pk_mul_f32 v[214:215], v[214:215], v[196:197] op_sel_hi:[1,0]
	v_pk_fma_f32 v[214:215], v[214:215], v[76:77], v[108:109]
	v_cvt_pk_bf16_f32 v127, v214, v215
	v_lshlrev_b32_e32 v216, 16, v128
	v_and_b32_e32 v217, 0xffff0000, v128
	v_pk_mul_f32 v[216:217], v[216:217], v[196:197] op_sel_hi:[1,0]
	v_pk_fma_f32 v[216:217], v[216:217], v[78:79], v[110:111]
	v_cvt_pk_bf16_f32 v128, v216, v217
	v_lshlrev_b32_e32 v218, 16, v129
	v_and_b32_e32 v219, 0xffff0000, v129
	v_pk_mul_f32 v[218:219], v[218:219], v[196:197] op_sel_hi:[1,0]
	v_pk_fma_f32 v[218:219], v[218:219], v[80:81], v[112:113]
	v_cvt_pk_bf16_f32 v129, v218, v219
	global_store_dwordx4 v[186:187], v[122:125], off
	global_store_dwordx4 v[186:187], v[126:129], off offset:1024
	v_lshlrev_b32_e32 v212, 16, v130
	v_and_b32_e32 v213, 0xffff0000, v130
	v_pk_mul_f32 v[212:213], v[212:213], v[198:199] op_sel_hi:[1,0]
	v_pk_fma_f32 v[212:213], v[212:213], v[66:67], v[98:99]
	v_cvt_pk_bf16_f32 v130, v212, v213
	v_lshlrev_b32_e32 v214, 16, v131
	v_and_b32_e32 v215, 0xffff0000, v131
	v_pk_mul_f32 v[214:215], v[214:215], v[198:199] op_sel_hi:[1,0]
	v_pk_fma_f32 v[214:215], v[214:215], v[68:69], v[100:101]
	v_cvt_pk_bf16_f32 v131, v214, v215
	v_lshlrev_b32_e32 v216, 16, v132
	v_and_b32_e32 v217, 0xffff0000, v132
	v_pk_mul_f32 v[216:217], v[216:217], v[198:199] op_sel_hi:[1,0]
	v_pk_fma_f32 v[216:217], v[216:217], v[70:71], v[102:103]
	v_cvt_pk_bf16_f32 v132, v216, v217
	v_lshlrev_b32_e32 v218, 16, v133
	v_and_b32_e32 v219, 0xffff0000, v133
	v_pk_mul_f32 v[218:219], v[218:219], v[198:199] op_sel_hi:[1,0]
	v_pk_fma_f32 v[218:219], v[218:219], v[72:73], v[104:105]
	v_cvt_pk_bf16_f32 v133, v218, v219
	v_lshlrev_b32_e32 v212, 16, v134
	v_and_b32_e32 v213, 0xffff0000, v134
	v_pk_mul_f32 v[212:213], v[212:213], v[198:199] op_sel_hi:[1,0]
	v_pk_fma_f32 v[212:213], v[212:213], v[74:75], v[106:107]
	v_cvt_pk_bf16_f32 v134, v212, v213
	v_lshlrev_b32_e32 v214, 16, v135
	v_and_b32_e32 v215, 0xffff0000, v135
	v_pk_mul_f32 v[214:215], v[214:215], v[198:199] op_sel_hi:[1,0]
	v_pk_fma_f32 v[214:215], v[214:215], v[76:77], v[108:109]
	v_cvt_pk_bf16_f32 v135, v214, v215
	v_lshlrev_b32_e32 v216, 16, v136
	v_and_b32_e32 v217, 0xffff0000, v136
	v_pk_mul_f32 v[216:217], v[216:217], v[198:199] op_sel_hi:[1,0]
	v_pk_fma_f32 v[216:217], v[216:217], v[78:79], v[110:111]
	v_cvt_pk_bf16_f32 v136, v216, v217
	v_lshlrev_b32_e32 v218, 16, v137
	v_and_b32_e32 v219, 0xffff0000, v137
	v_pk_mul_f32 v[218:219], v[218:219], v[198:199] op_sel_hi:[1,0]
	v_pk_fma_f32 v[218:219], v[218:219], v[80:81], v[112:113]
	v_cvt_pk_bf16_f32 v137, v218, v219
	global_store_dwordx4 v[186:187], v[130:133], off offset:2048
	global_store_dwordx4 v[186:187], v[134:137], off offset:3072
	v_lshlrev_b32_e32 v212, 16, v138
	v_and_b32_e32 v213, 0xffff0000, v138
	v_pk_mul_f32 v[212:213], v[212:213], v[200:201] op_sel_hi:[1,0]
	v_pk_fma_f32 v[212:213], v[212:213], v[66:67], v[98:99]
	v_cvt_pk_bf16_f32 v138, v212, v213
	v_lshlrev_b32_e32 v214, 16, v139
	v_and_b32_e32 v215, 0xffff0000, v139
	v_pk_mul_f32 v[214:215], v[214:215], v[200:201] op_sel_hi:[1,0]
	v_pk_fma_f32 v[214:215], v[214:215], v[68:69], v[100:101]
	v_cvt_pk_bf16_f32 v139, v214, v215
	v_lshlrev_b32_e32 v216, 16, v140
	v_and_b32_e32 v217, 0xffff0000, v140
	v_pk_mul_f32 v[216:217], v[216:217], v[200:201] op_sel_hi:[1,0]
	v_pk_fma_f32 v[216:217], v[216:217], v[70:71], v[102:103]
	v_cvt_pk_bf16_f32 v140, v216, v217
	v_lshlrev_b32_e32 v218, 16, v141
	v_and_b32_e32 v219, 0xffff0000, v141
	v_pk_mul_f32 v[218:219], v[218:219], v[200:201] op_sel_hi:[1,0]
	v_pk_fma_f32 v[218:219], v[218:219], v[72:73], v[104:105]
	v_cvt_pk_bf16_f32 v141, v218, v219
	v_lshlrev_b32_e32 v212, 16, v142
	v_and_b32_e32 v213, 0xffff0000, v142
	v_pk_mul_f32 v[212:213], v[212:213], v[200:201] op_sel_hi:[1,0]
	v_pk_fma_f32 v[212:213], v[212:213], v[74:75], v[106:107]
	v_cvt_pk_bf16_f32 v142, v212, v213
	v_lshlrev_b32_e32 v214, 16, v143
	v_and_b32_e32 v215, 0xffff0000, v143
	v_pk_mul_f32 v[214:215], v[214:215], v[200:201] op_sel_hi:[1,0]
	v_pk_fma_f32 v[214:215], v[214:215], v[76:77], v[108:109]
	v_cvt_pk_bf16_f32 v143, v214, v215
	v_lshlrev_b32_e32 v216, 16, v144
	v_and_b32_e32 v217, 0xffff0000, v144
	v_pk_mul_f32 v[216:217], v[216:217], v[200:201] op_sel_hi:[1,0]
	v_pk_fma_f32 v[216:217], v[216:217], v[78:79], v[110:111]
	v_cvt_pk_bf16_f32 v144, v216, v217
	v_lshlrev_b32_e32 v218, 16, v145
	v_and_b32_e32 v219, 0xffff0000, v145
	v_pk_mul_f32 v[218:219], v[218:219], v[200:201] op_sel_hi:[1,0]
	v_pk_fma_f32 v[218:219], v[218:219], v[80:81], v[112:113]
	v_cvt_pk_bf16_f32 v145, v218, v219
	global_store_dwordx4 v[188:189], v[138:141], off
	global_store_dwordx4 v[188:189], v[142:145], off offset:1024
	v_lshlrev_b32_e32 v212, 16, v146
	v_and_b32_e32 v213, 0xffff0000, v146
	v_pk_mul_f32 v[212:213], v[212:213], v[202:203] op_sel_hi:[1,0]
	v_pk_fma_f32 v[212:213], v[212:213], v[66:67], v[98:99]
	v_cvt_pk_bf16_f32 v146, v212, v213
	v_lshlrev_b32_e32 v214, 16, v147
	v_and_b32_e32 v215, 0xffff0000, v147
	v_pk_mul_f32 v[214:215], v[214:215], v[202:203] op_sel_hi:[1,0]
	v_pk_fma_f32 v[214:215], v[214:215], v[68:69], v[100:101]
	v_cvt_pk_bf16_f32 v147, v214, v215
	v_lshlrev_b32_e32 v216, 16, v148
	v_and_b32_e32 v217, 0xffff0000, v148
	v_pk_mul_f32 v[216:217], v[216:217], v[202:203] op_sel_hi:[1,0]
	v_pk_fma_f32 v[216:217], v[216:217], v[70:71], v[102:103]
	v_cvt_pk_bf16_f32 v148, v216, v217
	v_lshlrev_b32_e32 v218, 16, v149
	v_and_b32_e32 v219, 0xffff0000, v149
	v_pk_mul_f32 v[218:219], v[218:219], v[202:203] op_sel_hi:[1,0]
	v_pk_fma_f32 v[218:219], v[218:219], v[72:73], v[104:105]
	v_cvt_pk_bf16_f32 v149, v218, v219
	v_lshlrev_b32_e32 v212, 16, v150
	v_and_b32_e32 v213, 0xffff0000, v150
	v_pk_mul_f32 v[212:213], v[212:213], v[202:203] op_sel_hi:[1,0]
	v_pk_fma_f32 v[212:213], v[212:213], v[74:75], v[106:107]
	v_cvt_pk_bf16_f32 v150, v212, v213
	v_lshlrev_b32_e32 v214, 16, v151
	v_and_b32_e32 v215, 0xffff0000, v151
	v_pk_mul_f32 v[214:215], v[214:215], v[202:203] op_sel_hi:[1,0]
	v_pk_fma_f32 v[214:215], v[214:215], v[76:77], v[108:109]
	v_cvt_pk_bf16_f32 v151, v214, v215
	v_lshlrev_b32_e32 v216, 16, v152
	v_and_b32_e32 v217, 0xffff0000, v152
	v_pk_mul_f32 v[216:217], v[216:217], v[202:203] op_sel_hi:[1,0]
	v_pk_fma_f32 v[216:217], v[216:217], v[78:79], v[110:111]
	v_cvt_pk_bf16_f32 v152, v216, v217
	v_lshlrev_b32_e32 v218, 16, v153
	v_and_b32_e32 v219, 0xffff0000, v153
	v_pk_mul_f32 v[218:219], v[218:219], v[202:203] op_sel_hi:[1,0]
	v_pk_fma_f32 v[218:219], v[218:219], v[80:81], v[112:113]
	v_cvt_pk_bf16_f32 v153, v218, v219
	global_store_dwordx4 v[188:189], v[146:149], off offset:2048
	global_store_dwordx4 v[188:189], v[150:153], off offset:3072
	v_lshlrev_b32_e32 v212, 16, v154
	v_and_b32_e32 v213, 0xffff0000, v154
	v_pk_mul_f32 v[212:213], v[212:213], v[204:205] op_sel_hi:[1,0]
	v_pk_fma_f32 v[212:213], v[212:213], v[66:67], v[98:99]
	v_cvt_pk_bf16_f32 v154, v212, v213
	v_lshlrev_b32_e32 v214, 16, v155
	v_and_b32_e32 v215, 0xffff0000, v155
	v_pk_mul_f32 v[214:215], v[214:215], v[204:205] op_sel_hi:[1,0]
	v_pk_fma_f32 v[214:215], v[214:215], v[68:69], v[100:101]
	v_cvt_pk_bf16_f32 v155, v214, v215
	v_lshlrev_b32_e32 v216, 16, v156
	v_and_b32_e32 v217, 0xffff0000, v156
	v_pk_mul_f32 v[216:217], v[216:217], v[204:205] op_sel_hi:[1,0]
	v_pk_fma_f32 v[216:217], v[216:217], v[70:71], v[102:103]
	v_cvt_pk_bf16_f32 v156, v216, v217
	v_lshlrev_b32_e32 v218, 16, v157
	v_and_b32_e32 v219, 0xffff0000, v157
	v_pk_mul_f32 v[218:219], v[218:219], v[204:205] op_sel_hi:[1,0]
	v_pk_fma_f32 v[218:219], v[218:219], v[72:73], v[104:105]
	v_cvt_pk_bf16_f32 v157, v218, v219
	v_lshlrev_b32_e32 v212, 16, v158
	v_and_b32_e32 v213, 0xffff0000, v158
	v_pk_mul_f32 v[212:213], v[212:213], v[204:205] op_sel_hi:[1,0]
	v_pk_fma_f32 v[212:213], v[212:213], v[74:75], v[106:107]
	v_cvt_pk_bf16_f32 v158, v212, v213
	v_lshlrev_b32_e32 v214, 16, v159
	v_and_b32_e32 v215, 0xffff0000, v159
	v_pk_mul_f32 v[214:215], v[214:215], v[204:205] op_sel_hi:[1,0]
	v_pk_fma_f32 v[214:215], v[214:215], v[76:77], v[108:109]
	v_cvt_pk_bf16_f32 v159, v214, v215
	v_lshlrev_b32_e32 v216, 16, v160
	v_and_b32_e32 v217, 0xffff0000, v160
	v_pk_mul_f32 v[216:217], v[216:217], v[204:205] op_sel_hi:[1,0]
	v_pk_fma_f32 v[216:217], v[216:217], v[78:79], v[110:111]
	v_cvt_pk_bf16_f32 v160, v216, v217
	v_lshlrev_b32_e32 v218, 16, v161
	v_and_b32_e32 v219, 0xffff0000, v161
	v_pk_mul_f32 v[218:219], v[218:219], v[204:205] op_sel_hi:[1,0]
	v_pk_fma_f32 v[218:219], v[218:219], v[80:81], v[112:113]
	v_cvt_pk_bf16_f32 v161, v218, v219
	global_store_dwordx4 v[190:191], v[154:157], off
	global_store_dwordx4 v[190:191], v[158:161], off offset:1024
	v_lshlrev_b32_e32 v212, 16, v162
	v_and_b32_e32 v213, 0xffff0000, v162
	v_pk_mul_f32 v[212:213], v[212:213], v[206:207] op_sel_hi:[1,0]
	v_pk_fma_f32 v[212:213], v[212:213], v[66:67], v[98:99]
	v_cvt_pk_bf16_f32 v162, v212, v213
	v_lshlrev_b32_e32 v214, 16, v163
	v_and_b32_e32 v215, 0xffff0000, v163
	v_pk_mul_f32 v[214:215], v[214:215], v[206:207] op_sel_hi:[1,0]
	v_pk_fma_f32 v[214:215], v[214:215], v[68:69], v[100:101]
	v_cvt_pk_bf16_f32 v163, v214, v215
	v_lshlrev_b32_e32 v216, 16, v164
	v_and_b32_e32 v217, 0xffff0000, v164
	v_pk_mul_f32 v[216:217], v[216:217], v[206:207] op_sel_hi:[1,0]
	v_pk_fma_f32 v[216:217], v[216:217], v[70:71], v[102:103]
	v_cvt_pk_bf16_f32 v164, v216, v217
	v_lshlrev_b32_e32 v218, 16, v165
	v_and_b32_e32 v219, 0xffff0000, v165
	v_pk_mul_f32 v[218:219], v[218:219], v[206:207] op_sel_hi:[1,0]
	v_pk_fma_f32 v[218:219], v[218:219], v[72:73], v[104:105]
	v_cvt_pk_bf16_f32 v165, v218, v219
	v_lshlrev_b32_e32 v212, 16, v166
	v_and_b32_e32 v213, 0xffff0000, v166
	v_pk_mul_f32 v[212:213], v[212:213], v[206:207] op_sel_hi:[1,0]
	v_pk_fma_f32 v[212:213], v[212:213], v[74:75], v[106:107]
	v_cvt_pk_bf16_f32 v166, v212, v213
	v_lshlrev_b32_e32 v214, 16, v167
	v_and_b32_e32 v215, 0xffff0000, v167
	v_pk_mul_f32 v[214:215], v[214:215], v[206:207] op_sel_hi:[1,0]
	v_pk_fma_f32 v[214:215], v[214:215], v[76:77], v[108:109]
	v_cvt_pk_bf16_f32 v167, v214, v215
	v_lshlrev_b32_e32 v216, 16, v168
	v_and_b32_e32 v217, 0xffff0000, v168
	v_pk_mul_f32 v[216:217], v[216:217], v[206:207] op_sel_hi:[1,0]
	v_pk_fma_f32 v[216:217], v[216:217], v[78:79], v[110:111]
	v_cvt_pk_bf16_f32 v168, v216, v217
	v_lshlrev_b32_e32 v218, 16, v169
	v_and_b32_e32 v219, 0xffff0000, v169
	v_pk_mul_f32 v[218:219], v[218:219], v[206:207] op_sel_hi:[1,0]
	v_pk_fma_f32 v[218:219], v[218:219], v[80:81], v[112:113]
	v_cvt_pk_bf16_f32 v169, v218, v219
	global_store_dwordx4 v[190:191], v[162:165], off offset:2048
	global_store_dwordx4 v[190:191], v[166:169], off offset:3072
	v_lshlrev_b32_e32 v212, 16, v170
	v_and_b32_e32 v213, 0xffff0000, v170
	v_pk_mul_f32 v[212:213], v[212:213], v[208:209] op_sel_hi:[1,0]
	v_pk_fma_f32 v[212:213], v[212:213], v[66:67], v[98:99]
	v_cvt_pk_bf16_f32 v170, v212, v213
	v_lshlrev_b32_e32 v214, 16, v171
	v_and_b32_e32 v215, 0xffff0000, v171
	v_pk_mul_f32 v[214:215], v[214:215], v[208:209] op_sel_hi:[1,0]
	v_pk_fma_f32 v[214:215], v[214:215], v[68:69], v[100:101]
	v_cvt_pk_bf16_f32 v171, v214, v215
	v_lshlrev_b32_e32 v216, 16, v172
	v_and_b32_e32 v217, 0xffff0000, v172
	v_pk_mul_f32 v[216:217], v[216:217], v[208:209] op_sel_hi:[1,0]
	v_pk_fma_f32 v[216:217], v[216:217], v[70:71], v[102:103]
	v_cvt_pk_bf16_f32 v172, v216, v217
	v_lshlrev_b32_e32 v218, 16, v173
	v_and_b32_e32 v219, 0xffff0000, v173
	v_pk_mul_f32 v[218:219], v[218:219], v[208:209] op_sel_hi:[1,0]
	v_pk_fma_f32 v[218:219], v[218:219], v[72:73], v[104:105]
	v_cvt_pk_bf16_f32 v173, v218, v219
	v_lshlrev_b32_e32 v212, 16, v174
	v_and_b32_e32 v213, 0xffff0000, v174
	v_pk_mul_f32 v[212:213], v[212:213], v[208:209] op_sel_hi:[1,0]
	v_pk_fma_f32 v[212:213], v[212:213], v[74:75], v[106:107]
	v_cvt_pk_bf16_f32 v174, v212, v213
	v_lshlrev_b32_e32 v214, 16, v175
	v_and_b32_e32 v215, 0xffff0000, v175
	v_pk_mul_f32 v[214:215], v[214:215], v[208:209] op_sel_hi:[1,0]
	v_pk_fma_f32 v[214:215], v[214:215], v[76:77], v[108:109]
	v_cvt_pk_bf16_f32 v175, v214, v215
	v_lshlrev_b32_e32 v216, 16, v176
	v_and_b32_e32 v217, 0xffff0000, v176
	v_pk_mul_f32 v[216:217], v[216:217], v[208:209] op_sel_hi:[1,0]
	v_pk_fma_f32 v[216:217], v[216:217], v[78:79], v[110:111]
	v_cvt_pk_bf16_f32 v176, v216, v217
	v_lshlrev_b32_e32 v218, 16, v177
	v_and_b32_e32 v219, 0xffff0000, v177
	v_pk_mul_f32 v[218:219], v[218:219], v[208:209] op_sel_hi:[1,0]
	v_pk_fma_f32 v[218:219], v[218:219], v[80:81], v[112:113]
	v_cvt_pk_bf16_f32 v177, v218, v219
	global_store_dwordx4 v[192:193], v[170:173], off
	global_store_dwordx4 v[192:193], v[174:177], off offset:1024
	v_lshlrev_b32_e32 v212, 16, v178
	v_and_b32_e32 v213, 0xffff0000, v178
	v_pk_mul_f32 v[212:213], v[212:213], v[210:211] op_sel_hi:[1,0]
	v_pk_fma_f32 v[212:213], v[212:213], v[66:67], v[98:99]
	v_cvt_pk_bf16_f32 v178, v212, v213
	v_lshlrev_b32_e32 v214, 16, v179
	v_and_b32_e32 v215, 0xffff0000, v179
	v_pk_mul_f32 v[214:215], v[214:215], v[210:211] op_sel_hi:[1,0]
	v_pk_fma_f32 v[214:215], v[214:215], v[68:69], v[100:101]
	v_cvt_pk_bf16_f32 v179, v214, v215
	v_lshlrev_b32_e32 v216, 16, v180
	v_and_b32_e32 v217, 0xffff0000, v180
	v_pk_mul_f32 v[216:217], v[216:217], v[210:211] op_sel_hi:[1,0]
	v_pk_fma_f32 v[216:217], v[216:217], v[70:71], v[102:103]
	v_cvt_pk_bf16_f32 v180, v216, v217
	v_lshlrev_b32_e32 v218, 16, v181
	v_and_b32_e32 v219, 0xffff0000, v181
	v_pk_mul_f32 v[218:219], v[218:219], v[210:211] op_sel_hi:[1,0]
	v_pk_fma_f32 v[218:219], v[218:219], v[72:73], v[104:105]
	v_cvt_pk_bf16_f32 v181, v218, v219
	v_lshlrev_b32_e32 v212, 16, v182
	v_and_b32_e32 v213, 0xffff0000, v182
	v_pk_mul_f32 v[212:213], v[212:213], v[210:211] op_sel_hi:[1,0]
	v_pk_fma_f32 v[212:213], v[212:213], v[74:75], v[106:107]
	v_cvt_pk_bf16_f32 v182, v212, v213
	v_lshlrev_b32_e32 v214, 16, v183
	v_and_b32_e32 v215, 0xffff0000, v183
	v_pk_mul_f32 v[214:215], v[214:215], v[210:211] op_sel_hi:[1,0]
	v_pk_fma_f32 v[214:215], v[214:215], v[76:77], v[108:109]
	v_cvt_pk_bf16_f32 v183, v214, v215
	v_lshlrev_b32_e32 v216, 16, v184
	v_and_b32_e32 v217, 0xffff0000, v184
	v_pk_mul_f32 v[216:217], v[216:217], v[210:211] op_sel_hi:[1,0]
	v_pk_fma_f32 v[216:217], v[216:217], v[78:79], v[110:111]
	v_cvt_pk_bf16_f32 v184, v216, v217
	v_lshlrev_b32_e32 v218, 16, v185
	v_and_b32_e32 v219, 0xffff0000, v185
	v_pk_mul_f32 v[218:219], v[218:219], v[210:211] op_sel_hi:[1,0]
	v_pk_fma_f32 v[218:219], v[218:219], v[80:81], v[112:113]
	v_cvt_pk_bf16_f32 v185, v218, v219
	global_store_dwordx4 v[192:193], v[178:181], off offset:2048
	global_store_dwordx4 v[192:193], v[182:185], off offset:3072
	s_mov_b32 s23, s22

.LBB0_656:
	s_cmpk_eq_i32 s46, 0x100
	s_cbranch_scc1 .LBB0_659
	s_mov_b32 s8, 20
	v_readfirstlane_b32 s2, v224
	s_ashr_i32 s2, s2, 6
	s_add_i32 s2, s2, s92
	s_mov_b32 s6, 19
	s_mov_b32 s4, 18
	s_cmpk_gt_i32 s2, 0x3fff
	s_cbranch_scc1 .LBB0_659
	s_ashr_i32 s9, s8, 31
	s_lshl_b64 s[8:9], s[8:9], 3
	s_add_u32 s8, s0, s8
	s_addc_u32 s9, s1, s9
	s_ashr_i32 s7, s6, 31
	s_lshl_b64 s[6:7], s[6:7], 3
	s_add_u32 s6, s0, s6
	s_addc_u32 s7, s1, s7
	s_ashr_i32 s5, s4, 31
	s_lshl_b64 s[4:5], s[4:5], 3
	s_add_u32 s0, s0, s4
	s_addc_u32 s1, s1, s5
	s_load_dwordx2 s[0:1], s[0:1], 0x0
	v_lshlrev_b32_e32 v0, 4, v224
	v_and_b32_e32 v16, 0x3f0, v0
	s_waitcnt lgkmcnt(0)
	global_load_dwordx4 v[0:3], v16, s[0:1]
	global_load_dwordx4 v[4:7], v16, s[0:1] offset:1024
	global_load_dwordx4 v[8:11], v16, s[0:1] offset:2048
	global_load_dwordx4 v[12:15], v16, s[0:1] offset:3072
	v_and_b32_e32 v16, 64, v226
	v_add_u32_e32 v16, 64, v16
	v_xor_b32_e32 v17, 1, v226
	v_cmp_lt_i32_e32 vcc, v17, v16
	s_load_dwordx2 s[0:1], s[8:9], 0x0
	s_load_dwordx2 s[10:11], s[6:7], 0x0
	v_cndmask_b32_e32 v17, v226, v17, vcc
	v_lshlrev_b32_e32 v20, 2, v17
	v_xor_b32_e32 v17, 2, v226
	v_cmp_lt_i32_e32 vcc, v17, v16
	s_ashr_i32 s3, s2, 31
	s_lshl_b64 s[4:5], s[2:3], 11
	v_cndmask_b32_e32 v17, v226, v17, vcc
	v_lshlrev_b32_e32 v21, 2, v17
	v_xor_b32_e32 v17, 4, v226
	v_cmp_lt_i32_e32 vcc, v17, v16
	v_and_b32_e32 v26, 63, v224
	s_waitcnt lgkmcnt(0)
	s_add_u32 s0, s0, s4
	v_cndmask_b32_e32 v17, v226, v17, vcc
	v_lshlrev_b32_e32 v22, 2, v17
	v_xor_b32_e32 v17, 8, v226
	v_cmp_lt_i32_e32 vcc, v17, v16
	v_lshlrev_b32_e32 v18, 3, v26
	v_mov_b32_e32 v19, 0
	v_cndmask_b32_e32 v17, v226, v17, vcc
	v_lshlrev_b32_e32 v23, 2, v17
	v_xor_b32_e32 v17, 16, v226
	v_cmp_lt_i32_e32 vcc, v17, v16
	s_addc_u32 s1, s1, s5
	s_ashr_i32 s49, s48, 31
	v_cndmask_b32_e32 v17, v226, v17, vcc
	v_lshlrev_b32_e32 v24, 2, v17
	v_xor_b32_e32 v17, 32, v226
	v_cmp_lt_i32_e32 vcc, v17, v16
	s_lshl_b64 s[4:5], s[48:49], 11
	v_mov_b32_e32 v27, 0x260
	v_cndmask_b32_e32 v16, v226, v17, vcc
	v_lshlrev_b32_e32 v25, 2, v16
	v_lshl_add_u64 v[16:17], s[0:1], 0, v[18:19]
	s_mov_b64 s[0:1], 0x4c00000
	v_lshl_add_u64 v[16:17], v[16:17], 0, s[0:1]
	s_lshl_b64 s[0:1], s[2:3], 12
	s_add_u32 s0, s10, s0
	v_lshlrev_b32_e32 v18, 4, v26
	s_addc_u32 s1, s11, s1
	v_lshl_add_u64 v[18:19], s[0:1], 0, v[18:19]
	s_mov_b64 s[0:1], 0xc00
	v_lshl_add_u64 v[18:19], v[18:19], 0, s[0:1]
	s_lshl_b64 s[6:7], s[48:49], 12
	v_mov_b32_e32 v26, 0x358637bd
	s_mov_b32 s3, 0xf800000
